# GEMM K-loops: one s_setprio window per MFMA phase (mid-phase 0/1 toggle removed), duplicate lgkmcnt(0) after phase barrier removed
# speedup vs baseline: 1.0055x; 1.0055x over previous
; #define PG8_STAGE(bufoff, gbase, voff) do { _Pragma("unroll") for (int _i = 0; _i < 2; ++_i) \
;         __builtin_amdgcn_global_load_lds((const unsigned*)((const char*)(gbase) + (voff)[_i]), (PG8_LAS unsigned*)(lds + (bufoff) + ldsw + _i * 8192), 16, 0, 0); } while (0)
; #define PG8_LDA(dst, b, h) do { _Pragma("unroll") for (int m = 0; m < 4; ++m) _Pragma("unroll") for (int k = 0; k < 2; ++k) dst[m][k] = *(const PG8_LAS bf16x8*)(lds + PG8_SA(b, h) + aoff + m * 2048 + k * 1024); } while (0)
; #define PG8_LDB(dst, b, h) do { _Pragma("unroll") for (int n = 0; n < 2; ++n) _Pragma("unroll") for (int k = 0; k < 2; ++k) dst[n][k] = *(const PG8_LAS bf16x8*)(lds + PG8_SB(b, h) + boff + n * 2048 + k * 1024); } while (0)
; #define PG8_MMA(ai, bj, At, Bt) do { __builtin_amdgcn_s_setprio(1); _Pragma("unroll") for (int m = 0; m < 4; ++m) _Pragma("unroll") for (int n = 0; n < 2; ++n) _Pragma("unroll") for (int k = 0; k < 2; ++k) \
;         acc[ai][bj][m][n] = __builtin_amdgcn_mfma_f32_16x16x32_bf16(Bt[n][k], At[m][k], acc[ai][bj][m][n], 0, 0, 0); __builtin_amdgcn_s_setprio(0); } while (0)
; #define PG8_WAIT_V(n) asm volatile("s_waitcnt vmcnt(" #n ")" ::: "memory")
; #define PG8_WAIT_L(n) asm volatile("s_waitcnt lgkmcnt(" #n ")" ::: "memory")
; template <class Epi, class Sched, bool ALIGN_EPI = false, bool SP2 = false>
; __device__ __forceinline__ void gemm_phase(PG8_LAS unsigned char* lds, const Gemm g, const Sched& S, const Epi& E, const int tid) {
;     ...
;             const bool last = (t == nt - 2);
;             const char* a1 = cA + (size_t)(t + 1) * kstep;
;             const char* a2 = last ? nA : cA + (size_t)(t + 2) * kstep; const char* b2 = last ? nB : cB + (size_t)(t + 2) * kstep;
;             const char* a3 = a2 + kstep; const char* b3 = b2 + kstep;
;             if (last && has_next) S.a_ready(nxt);
;             if constexpr (SP2) {
;             PG8_LDB(B0, 0, 0); PG8_LDB(B1, 0, 1); PG8_SCHED; PG8_LDA(At, 0, 0); PG8_STAGE(PG8_SA(1, 1), a1 + hstep, voffA);
;             PG8_WAIT_V(8); PG8_WAIT_L(0); PG8_BAR; PG8_MMA(0, 0, At, B0); PG8_MMA(0, 1, At, B1); PG8_BAR; PG8_SCHED;
;             PG8_LDA(At, 0, 1); PG8_STAGE(PG8_SB(0, 0), b2, voffB); PG8_STAGE(PG8_SB(0, 1), b2 + hstep, voffB); PG8_STAGE(PG8_SA(0, 0), a2, voffA);
;             PG8_WAIT_V(8); PG8_WAIT_L(0); PG8_BAR; PG8_MMA(1, 0, At, B0); PG8_MMA(1, 1, At, B1); PG8_BAR; PG8_SCHED;
.LBB0_211:
	s_add_u32 s56, s54, 0xfff80080
	s_addc_u32 s57, s55, -1
	s_add_i32 s78, 0, 0x10000
	s_cmp_eq_u32 s77, 28
	s_cselect_b32 s59, s49, s57
	s_cselect_b32 s58, s72, s56
	s_cselect_b32 s57, s47, s76
	s_cselect_b32 s56, s73, s75
	s_add_i32 s80, 0, 0x14000
	v_add_u32_e32 v154, s78, v160
	v_add_u32_e32 v158, s80, v160
	ds_read_b128 v[142:145], v154
	ds_read_b128 v[146:149], v154 offset:1024
	ds_read_b128 v[150:153], v154 offset:2048
	ds_read_b128 v[154:157], v154 offset:3072
	ds_read_b128 v[164:167], v158
	ds_read_b128 v[168:171], v158 offset:1024
	ds_read_b128 v[172:175], v158 offset:2048
	ds_read_b128 v[176:179], v158 offset:3072
	v_lshl_add_u64 v[158:159], s[54:55], 0, v[140:141]
	s_add_i32 m0, s61, 0xc000
	ds_read_b128 v[186:189], v162
	ds_read_b128 v[190:193], v162 offset:1024
	ds_read_b128 v[194:197], v162 offset:2048
	ds_read_b128 v[198:201], v162 offset:3072
	ds_read_b128 v[202:205], v162 offset:4096
	ds_read_b128 v[206:209], v162 offset:5120
	ds_read_b128 v[210:213], v162 offset:6144
	ds_read_b128 v[214:217], v162 offset:7168
	global_load_lds_dwordx4 v[158:159], off
	v_lshl_add_u64 v[158:159], s[54:55], 0, v[138:139]
	s_add_i32 m0, s61, 0xe000
	s_nop 0
	global_load_lds_dwordx4 v[158:159], off
	s_waitcnt vmcnt(8)
	s_waitcnt lgkmcnt(0)
	s_barrier
	s_setprio 1
	v_mfma_f32_16x16x32_bf16 v[130:133], v[142:145], v[186:189], v[130:133]
	v_mfma_f32_16x16x32_bf16 v[126:129], v[150:153], v[186:189], v[126:129]
	v_mfma_f32_16x16x32_bf16 v[114:117], v[142:145], v[194:197], v[114:117]
	v_mfma_f32_16x16x32_bf16 v[106:109], v[150:153], v[194:197], v[106:109]
	v_mfma_f32_16x16x32_bf16 v[92:95], v[142:145], v[202:205], v[92:95]
	v_mfma_f32_16x16x32_bf16 v[84:87], v[150:153], v[202:205], v[84:87]
	v_mfma_f32_16x16x32_bf16 v[76:79], v[142:145], v[210:213], v[76:79]
	v_mfma_f32_16x16x32_bf16 v[68:71], v[150:153], v[210:213], v[68:71]
	v_mfma_f32_16x16x32_bf16 v[130:133], v[146:149], v[190:193], v[130:133]
	v_mfma_f32_16x16x32_bf16 v[126:129], v[154:157], v[190:193], v[126:129]
	v_mfma_f32_16x16x32_bf16 v[114:117], v[146:149], v[198:201], v[114:117]
	v_mfma_f32_16x16x32_bf16 v[106:109], v[154:157], v[198:201], v[106:109]
	v_mfma_f32_16x16x32_bf16 v[92:95], v[146:149], v[206:209], v[92:95]
	v_mfma_f32_16x16x32_bf16 v[84:87], v[154:157], v[206:209], v[84:87]
	v_mfma_f32_16x16x32_bf16 v[76:79], v[146:149], v[214:217], v[76:79]
	v_mfma_f32_16x16x32_bf16 v[68:71], v[154:157], v[214:217], v[68:71]
	v_mfma_f32_16x16x32_bf16 v[122:125], v[164:167], v[186:189], v[122:125]
	v_mfma_f32_16x16x32_bf16 v[118:121], v[172:175], v[186:189], v[118:121]
	v_mfma_f32_16x16x32_bf16 v[110:113], v[164:167], v[194:197], v[110:113]
	v_mfma_f32_16x16x32_bf16 v[102:105], v[172:175], v[194:197], v[102:105]
	v_mfma_f32_16x16x32_bf16 v[88:91], v[164:167], v[202:205], v[88:91]
	v_mfma_f32_16x16x32_bf16 v[80:83], v[172:175], v[202:205], v[80:83]
	v_mfma_f32_16x16x32_bf16 v[72:75], v[164:167], v[210:213], v[72:75]
	v_mfma_f32_16x16x32_bf16 v[64:67], v[172:175], v[210:213], v[64:67]
	v_mfma_f32_16x16x32_bf16 v[122:125], v[168:171], v[190:193], v[122:125]
	v_mfma_f32_16x16x32_bf16 v[118:121], v[176:179], v[190:193], v[118:121]
	v_mfma_f32_16x16x32_bf16 v[110:113], v[168:171], v[198:201], v[110:113]
	v_mfma_f32_16x16x32_bf16 v[102:105], v[176:179], v[198:201], v[102:105]
	v_mfma_f32_16x16x32_bf16 v[88:91], v[168:171], v[206:209], v[88:91]
	v_mfma_f32_16x16x32_bf16 v[80:83], v[176:179], v[206:209], v[80:83]
	v_mfma_f32_16x16x32_bf16 v[72:75], v[168:171], v[214:217], v[72:75]
	v_mfma_f32_16x16x32_bf16 v[64:67], v[176:179], v[214:217], v[64:67]
	s_setprio 0
	s_barrier
	s_add_i32 s78, s78, s60
	v_lshl_add_u64 v[158:159], s[56:57], 0, v[96:97]
	s_mov_b32 m0, s78
	ds_read_b128 v[186:189], v162 offset:16384
	ds_read_b128 v[190:193], v162 offset:17408
	ds_read_b128 v[194:197], v162 offset:18432
	ds_read_b128 v[198:201], v162 offset:19456
	ds_read_b128 v[202:205], v162 offset:20480
	ds_read_b128 v[206:209], v162 offset:21504
	ds_read_b128 v[210:213], v162 offset:22528
	ds_read_b128 v[214:217], v162 offset:23552
	global_load_lds_dwordx4 v[158:159], off
	s_add_i32 m0, s78, 0x2000
	s_add_u32 s78, s56, 0x80000
	v_lshl_add_u64 v[180:181], s[56:57], 0, v[98:99]
	s_addc_u32 s79, s57, 0
	s_add_i32 s80, s80, s60
	global_load_lds_dwordx4 v[180:181], off
	v_lshl_add_u64 v[218:219], s[78:79], 0, v[96:97]
	s_mov_b32 m0, s80
	v_lshl_add_u64 v[220:221], s[58:59], 0, v[134:135]
	global_load_lds_dwordx4 v[218:219], off
	v_lshl_add_u64 v[218:219], s[78:79], 0, v[98:99]
	s_add_i32 m0, s80, 0x2000
	s_nop 0
	global_load_lds_dwordx4 v[218:219], off
	v_lshl_add_u64 v[218:219], s[58:59], 0, v[136:137]
	s_mov_b32 m0, s61
	s_nop 0
	global_load_lds_dwordx4 v[218:219], off
	s_mov_b32 m0, s64
	s_nop 0
	global_load_lds_dwordx4 v[220:221], off
	s_waitcnt vmcnt(8)
	s_waitcnt lgkmcnt(0)
	s_barrier
; #define PG8_STAGE(bufoff, gbase, voff) do { _Pragma("unroll") for (int _i = 0; _i < 2; ++_i) \
;         __builtin_amdgcn_global_load_lds((const unsigned*)((const char*)(gbase) + (voff)[_i]), (PG8_LAS unsigned*)(lds + (bufoff) + ldsw + _i * 8192), 16, 0, 0); } while (0)
; #define PG8_LDA(dst, b, h) do { _Pragma("unroll") for (int m = 0; m < 4; ++m) _Pragma("unroll") for (int k = 0; k < 2; ++k) dst[m][k] = *(const PG8_LAS bf16x8*)(lds + PG8_SA(b, h) + aoff + m * 2048 + k * 1024); } while (0)
; #define PG8_LDB(dst, b, h) do { _Pragma("unroll") for (int n = 0; n < 2; ++n) _Pragma("unroll") for (int k = 0; k < 2; ++k) dst[n][k] = *(const PG8_LAS bf16x8*)(lds + PG8_SB(b, h) + boff + n * 2048 + k * 1024); } while (0)
; #define PG8_MMA(ai, bj, At, Bt) do { __builtin_amdgcn_s_setprio(1); _Pragma("unroll") for (int m = 0; m < 4; ++m) _Pragma("unroll") for (int n = 0; n < 2; ++n) _Pragma("unroll") for (int k = 0; k < 2; ++k) \
;         acc[ai][bj][m][n] = __builtin_amdgcn_mfma_f32_16x16x32_bf16(Bt[n][k], At[m][k], acc[ai][bj][m][n], 0, 0, 0); __builtin_amdgcn_s_setprio(0); } while (0)
; #define PG8_WAIT_V(n) asm volatile("s_waitcnt vmcnt(" #n ")" ::: "memory")
; #define PG8_WAIT_L(n) asm volatile("s_waitcnt lgkmcnt(" #n ")" ::: "memory")
; #define PG8_BAR __builtin_amdgcn_s_barrier()
; #define PG8_SCHED __builtin_amdgcn_sched_barrier(0)
; template <class Epi, class Sched, bool ALIGN_EPI = false, bool SP2 = false>
; __device__ __forceinline__ void gemm_phase(PG8_LAS unsigned char* lds, const Gemm g, const Sched& S, const Epi& E, const int tid) {
;     ...
;             PG8_WAIT_V(8); PG8_WAIT_L(0); PG8_BAR; PG8_MMA(1, 0, At, B0); PG8_MMA(1, 1, At, B1); PG8_BAR; PG8_SCHED;
;             PG8_LDB(B0, 1, 0); PG8_LDB(B1, 1, 1); PG8_SCHED; PG8_LDA(At, 1, 0); PG8_STAGE(PG8_SA(0, 1), a2 + hstep, voffA);
;             PG8_WAIT_V(8); PG8_WAIT_L(0); PG8_BAR; PG8_MMA(0, 0, At, B0); PG8_MMA(0, 1, At, B1); PG8_BAR; PG8_SCHED;
	s_setprio 1
	v_mfma_f32_16x16x32_bf16 v[60:63], v[142:145], v[186:189], v[60:63]
	v_mfma_f32_16x16x32_bf16 v[52:55], v[150:153], v[186:189], v[52:55]
	v_mfma_f32_16x16x32_bf16 v[44:47], v[142:145], v[194:197], v[44:47]
	v_mfma_f32_16x16x32_bf16 v[36:39], v[150:153], v[194:197], v[36:39]
	v_mfma_f32_16x16x32_bf16 v[28:31], v[142:145], v[202:205], v[28:31]
	v_mfma_f32_16x16x32_bf16 v[20:23], v[150:153], v[202:205], v[20:23]
	v_mfma_f32_16x16x32_bf16 v[12:15], v[142:145], v[210:213], v[12:15]
	v_mfma_f32_16x16x32_bf16 v[4:7], v[150:153], v[210:213], v[4:7]
	v_mfma_f32_16x16x32_bf16 v[60:63], v[146:149], v[190:193], v[60:63]
	v_mfma_f32_16x16x32_bf16 v[52:55], v[154:157], v[190:193], v[52:55]
	v_mfma_f32_16x16x32_bf16 v[44:47], v[146:149], v[198:201], v[44:47]
	v_mfma_f32_16x16x32_bf16 v[36:39], v[154:157], v[198:201], v[36:39]
	v_mfma_f32_16x16x32_bf16 v[28:31], v[146:149], v[206:209], v[28:31]
	v_mfma_f32_16x16x32_bf16 v[20:23], v[154:157], v[206:209], v[20:23]
	v_mfma_f32_16x16x32_bf16 v[12:15], v[146:149], v[214:217], v[12:15]
	v_mfma_f32_16x16x32_bf16 v[4:7], v[154:157], v[214:217], v[4:7]
	v_mfma_f32_16x16x32_bf16 v[56:59], v[164:167], v[186:189], v[56:59]
	v_mfma_f32_16x16x32_bf16 v[48:51], v[172:175], v[186:189], v[48:51]
	v_mfma_f32_16x16x32_bf16 v[40:43], v[164:167], v[194:197], v[40:43]
	v_mfma_f32_16x16x32_bf16 v[32:35], v[172:175], v[194:197], v[32:35]
	v_mfma_f32_16x16x32_bf16 v[24:27], v[164:167], v[202:205], v[24:27]
	v_mfma_f32_16x16x32_bf16 v[16:19], v[172:175], v[202:205], v[16:19]
	v_mfma_f32_16x16x32_bf16 v[8:11], v[164:167], v[210:213], v[8:11]
	v_mfma_f32_16x16x32_bf16 v[0:3], v[172:175], v[210:213], v[0:3]
	v_mfma_f32_16x16x32_bf16 v[56:59], v[168:171], v[190:193], v[56:59]
	v_mfma_f32_16x16x32_bf16 v[48:51], v[176:179], v[190:193], v[48:51]
	v_mfma_f32_16x16x32_bf16 v[40:43], v[168:171], v[198:201], v[40:43]
	v_mfma_f32_16x16x32_bf16 v[32:35], v[176:179], v[198:201], v[32:35]
	v_mfma_f32_16x16x32_bf16 v[24:27], v[168:171], v[206:209], v[24:27]
	v_mfma_f32_16x16x32_bf16 v[16:19], v[176:179], v[206:209], v[16:19]
	v_mfma_f32_16x16x32_bf16 v[8:11], v[168:171], v[214:217], v[8:11]
	v_mfma_f32_16x16x32_bf16 v[0:3], v[176:179], v[214:217], v[0:3]
	s_setprio 0
	s_barrier
	s_add_i32 s78, 0, 0x18000
	s_add_i32 s79, 0, 0x1c000
	v_add_u32_e32 v154, s78, v160
	v_add_u32_e32 v163, s79, v160
	ds_read_b128 v[142:145], v154
	ds_read_b128 v[146:149], v154 offset:1024
	ds_read_b128 v[150:153], v154 offset:2048
	ds_read_b128 v[154:157], v154 offset:3072
	ds_read_b128 v[164:167], v163
	ds_read_b128 v[168:171], v163 offset:1024
	ds_read_b128 v[172:175], v163 offset:2048
	ds_read_b128 v[176:179], v163 offset:3072
	s_add_u32 s58, s58, 0x80000
	s_addc_u32 s59, s59, 0
	s_mov_b32 m0, s65
	v_lshl_add_u64 v[222:223], s[58:59], 0, v[136:137]
	ds_read_b128 v[186:189], v162 offset:32768
	ds_read_b128 v[190:193], v162 offset:33792
	ds_read_b128 v[194:197], v162 offset:34816
	ds_read_b128 v[198:201], v162 offset:35840
	ds_read_b128 v[202:205], v162 offset:36864
	ds_read_b128 v[206:209], v162 offset:37888
	ds_read_b128 v[210:213], v162 offset:38912
	ds_read_b128 v[214:217], v162 offset:39936
	global_load_lds_dwordx4 v[222:223], off
	v_lshl_add_u64 v[222:223], s[58:59], 0, v[134:135]
	s_mov_b32 m0, s66
	s_nop 0
	global_load_lds_dwordx4 v[222:223], off
	s_waitcnt vmcnt(8)
	s_waitcnt lgkmcnt(0)
	s_barrier
	s_setprio 1
	v_mfma_f32_16x16x32_bf16 v[130:133], v[142:145], v[186:189], v[130:133]
	v_mfma_f32_16x16x32_bf16 v[126:129], v[150:153], v[186:189], v[126:129]
	v_mfma_f32_16x16x32_bf16 v[114:117], v[142:145], v[194:197], v[114:117]
	v_mfma_f32_16x16x32_bf16 v[106:109], v[150:153], v[194:197], v[106:109]
	v_mfma_f32_16x16x32_bf16 v[92:95], v[142:145], v[202:205], v[92:95]
	v_mfma_f32_16x16x32_bf16 v[84:87], v[150:153], v[202:205], v[84:87]
	v_mfma_f32_16x16x32_bf16 v[76:79], v[142:145], v[210:213], v[76:79]
	v_mfma_f32_16x16x32_bf16 v[68:71], v[150:153], v[210:213], v[68:71]
	v_mfma_f32_16x16x32_bf16 v[130:133], v[146:149], v[190:193], v[130:133]
	v_mfma_f32_16x16x32_bf16 v[126:129], v[154:157], v[190:193], v[126:129]
	v_mfma_f32_16x16x32_bf16 v[114:117], v[146:149], v[198:201], v[114:117]
	v_mfma_f32_16x16x32_bf16 v[106:109], v[154:157], v[198:201], v[106:109]
	v_mfma_f32_16x16x32_bf16 v[92:95], v[146:149], v[206:209], v[92:95]
	v_mfma_f32_16x16x32_bf16 v[84:87], v[154:157], v[206:209], v[84:87]
	v_mfma_f32_16x16x32_bf16 v[76:79], v[146:149], v[214:217], v[76:79]
	v_mfma_f32_16x16x32_bf16 v[68:71], v[154:157], v[214:217], v[68:71]
	v_mfma_f32_16x16x32_bf16 v[122:125], v[164:167], v[186:189], v[122:125]
	v_mfma_f32_16x16x32_bf16 v[118:121], v[172:175], v[186:189], v[118:121]
	v_mfma_f32_16x16x32_bf16 v[110:113], v[164:167], v[194:197], v[110:113]
	v_mfma_f32_16x16x32_bf16 v[102:105], v[172:175], v[194:197], v[102:105]
	v_mfma_f32_16x16x32_bf16 v[88:91], v[164:167], v[202:205], v[88:91]
	v_mfma_f32_16x16x32_bf16 v[80:83], v[172:175], v[202:205], v[80:83]
	v_mfma_f32_16x16x32_bf16 v[72:75], v[164:167], v[210:213], v[72:75]
	v_mfma_f32_16x16x32_bf16 v[64:67], v[172:175], v[210:213], v[64:67]
	v_mfma_f32_16x16x32_bf16 v[122:125], v[168:171], v[190:193], v[122:125]
	v_mfma_f32_16x16x32_bf16 v[118:121], v[176:179], v[190:193], v[118:121]
	v_mfma_f32_16x16x32_bf16 v[110:113], v[168:171], v[198:201], v[110:113]
	v_mfma_f32_16x16x32_bf16 v[102:105], v[176:179], v[198:201], v[102:105]
	v_mfma_f32_16x16x32_bf16 v[88:91], v[168:171], v[206:209], v[88:91]
	v_mfma_f32_16x16x32_bf16 v[80:83], v[176:179], v[206:209], v[80:83]
	v_mfma_f32_16x16x32_bf16 v[72:75], v[168:171], v[214:217], v[72:75]
	v_mfma_f32_16x16x32_bf16 v[64:67], v[176:179], v[214:217], v[64:67]
	s_setprio 0
	s_barrier
; #define PG8_STAGE(bufoff, gbase, voff) do { _Pragma("unroll") for (int _i = 0; _i < 2; ++_i) \
;         __builtin_amdgcn_global_load_lds((const unsigned*)((const char*)(gbase) + (voff)[_i]), (PG8_LAS unsigned*)(lds + (bufoff) + ldsw + _i * 8192), 16, 0, 0); } while (0)
; #define PG8_LDA(dst, b, h) do { _Pragma("unroll") for (int m = 0; m < 4; ++m) _Pragma("unroll") for (int k = 0; k < 2; ++k) dst[m][k] = *(const PG8_LAS bf16x8*)(lds + PG8_SA(b, h) + aoff + m * 2048 + k * 1024); } while (0)
; #define PG8_MMA(ai, bj, At, Bt) do { __builtin_amdgcn_s_setprio(1); _Pragma("unroll") for (int m = 0; m < 4; ++m) _Pragma("unroll") for (int n = 0; n < 2; ++n) _Pragma("unroll") for (int k = 0; k < 2; ++k) \
;         acc[ai][bj][m][n] = __builtin_amdgcn_mfma_f32_16x16x32_bf16(Bt[n][k], At[m][k], acc[ai][bj][m][n], 0, 0, 0); __builtin_amdgcn_s_setprio(0); } while (0)
; #define PG8_WAIT_V(n) asm volatile("s_waitcnt vmcnt(" #n ")" ::: "memory")
; #define PG8_WAIT_L(n) asm volatile("s_waitcnt lgkmcnt(" #n ")" ::: "memory")
; #define PG8_BAR __builtin_amdgcn_s_barrier()
; #define PG8_SCHED __builtin_amdgcn_sched_barrier(0)
; template <class Epi, class Sched, bool ALIGN_EPI = false, bool SP2 = false>
; __device__ __forceinline__ void gemm_phase(PG8_LAS unsigned char* lds, const Gemm g, const Sched& S, const Epi& E, const int tid) {
;     ...
;             PG8_LDA(At, 1, 1); PG8_STAGE(PG8_SB(1, 0), b3, voffB); PG8_STAGE(PG8_SB(1, 1), b3 + hstep, voffB); PG8_STAGE(PG8_SA(1, 0), a3, voffA);
;             PG8_WAIT_V(8); PG8_WAIT_L(0); PG8_BAR; PG8_MMA(1, 0, At, B0); PG8_MMA(1, 1, At, B1); PG8_BAR; PG8_SCHED;
	s_add_i32 s58, s78, s60
	v_lshl_add_u64 v[158:159], v[158:159], 0, s[28:29]
	s_mov_b32 m0, s58
	ds_read_b128 v[186:189], v162 offset:49152
	ds_read_b128 v[190:193], v162 offset:50176
	ds_read_b128 v[194:197], v162 offset:51200
	ds_read_b128 v[198:201], v162 offset:52224
	ds_read_b128 v[202:205], v162 offset:53248
	ds_read_b128 v[206:209], v162 offset:54272
	ds_read_b128 v[210:213], v162 offset:55296
	ds_read_b128 v[214:217], v162 offset:56320
	global_load_lds_dwordx4 v[158:159], off
	s_add_i32 m0, s58, 0x2000
	s_add_u32 s56, s56, 0x80080
	v_lshl_add_u64 v[158:159], v[180:181], 0, s[28:29]
	s_addc_u32 s57, s57, 0
	s_add_i32 s58, s79, s60
	global_load_lds_dwordx4 v[158:159], off
	v_lshl_add_u64 v[158:159], s[56:57], 0, v[96:97]
	s_mov_b32 m0, s58
	s_nop 0
	global_load_lds_dwordx4 v[158:159], off
	v_lshl_add_u64 v[158:159], s[56:57], 0, v[98:99]
	s_add_i32 m0, s58, 0x2000
	s_nop 0
	global_load_lds_dwordx4 v[158:159], off
	v_lshl_add_u64 v[158:159], v[218:219], 0, s[28:29]
	s_mov_b32 m0, s67
	s_nop 0
	global_load_lds_dwordx4 v[158:159], off
	v_lshl_add_u64 v[158:159], v[220:221], 0, s[28:29]
	s_mov_b32 m0, s68
	s_nop 0
	global_load_lds_dwordx4 v[158:159], off
	s_waitcnt vmcnt(8)
	s_waitcnt lgkmcnt(0)
	s_barrier
	s_setprio 1
	v_mfma_f32_16x16x32_bf16 v[60:63], v[142:145], v[186:189], v[60:63]
	v_mfma_f32_16x16x32_bf16 v[52:55], v[150:153], v[186:189], v[52:55]
	v_mfma_f32_16x16x32_bf16 v[44:47], v[142:145], v[194:197], v[44:47]
	v_mfma_f32_16x16x32_bf16 v[36:39], v[150:153], v[194:197], v[36:39]
	v_mfma_f32_16x16x32_bf16 v[28:31], v[142:145], v[202:205], v[28:31]
	v_mfma_f32_16x16x32_bf16 v[20:23], v[150:153], v[202:205], v[20:23]
	v_mfma_f32_16x16x32_bf16 v[12:15], v[142:145], v[210:213], v[12:15]
	v_mfma_f32_16x16x32_bf16 v[4:7], v[150:153], v[210:213], v[4:7]
	v_mfma_f32_16x16x32_bf16 v[60:63], v[146:149], v[190:193], v[60:63]
	v_mfma_f32_16x16x32_bf16 v[52:55], v[154:157], v[190:193], v[52:55]
	v_mfma_f32_16x16x32_bf16 v[44:47], v[146:149], v[198:201], v[44:47]
	v_mfma_f32_16x16x32_bf16 v[36:39], v[154:157], v[198:201], v[36:39]
	v_mfma_f32_16x16x32_bf16 v[28:31], v[146:149], v[206:209], v[28:31]
	v_mfma_f32_16x16x32_bf16 v[20:23], v[154:157], v[206:209], v[20:23]
	v_mfma_f32_16x16x32_bf16 v[12:15], v[146:149], v[214:217], v[12:15]
	v_mfma_f32_16x16x32_bf16 v[4:7], v[154:157], v[214:217], v[4:7]
	v_mfma_f32_16x16x32_bf16 v[56:59], v[164:167], v[186:189], v[56:59]
	v_mfma_f32_16x16x32_bf16 v[48:51], v[172:175], v[186:189], v[48:51]
	v_mfma_f32_16x16x32_bf16 v[40:43], v[164:167], v[194:197], v[40:43]
	v_mfma_f32_16x16x32_bf16 v[32:35], v[172:175], v[194:197], v[32:35]
	v_mfma_f32_16x16x32_bf16 v[24:27], v[164:167], v[202:205], v[24:27]
	v_mfma_f32_16x16x32_bf16 v[16:19], v[172:175], v[202:205], v[16:19]
	v_mfma_f32_16x16x32_bf16 v[8:11], v[164:167], v[210:213], v[8:11]
	v_mfma_f32_16x16x32_bf16 v[0:3], v[172:175], v[210:213], v[0:3]
	v_mfma_f32_16x16x32_bf16 v[56:59], v[168:171], v[190:193], v[56:59]
	v_mfma_f32_16x16x32_bf16 v[48:51], v[176:179], v[190:193], v[48:51]
	v_mfma_f32_16x16x32_bf16 v[40:43], v[168:171], v[198:201], v[40:43]
	v_mfma_f32_16x16x32_bf16 v[32:35], v[176:179], v[198:201], v[32:35]
	v_mfma_f32_16x16x32_bf16 v[24:27], v[168:171], v[206:209], v[24:27]
	v_mfma_f32_16x16x32_bf16 v[16:19], v[176:179], v[206:209], v[16:19]
	v_mfma_f32_16x16x32_bf16 v[8:11], v[168:171], v[214:217], v[8:11]
	v_mfma_f32_16x16x32_bf16 v[0:3], v[176:179], v[214:217], v[0:3]
	s_setprio 0
	s_barrier
	s_add_i32 s77, s77, 2
	s_add_u32 s75, s75, 0x100
	s_addc_u32 s76, s76, 0
	s_add_u32 s54, s54, 0x100
	s_addc_u32 s55, s55, 0
	s_cmp_gt_u32 s77, 29
	s_cbranch_scc0 .LBB0_211
	s_and_b64 vcc, exec, s[44:45]
	s_cbranch_vccz .LBB0_214
	s_barrier

; #define PG8_STAGE(bufoff, gbase, voff) do { _Pragma("unroll") for (int _i = 0; _i < 2; ++_i) \
;         __builtin_amdgcn_global_load_lds((const unsigned*)((const char*)(gbase) + (voff)[_i]), (PG8_LAS unsigned*)(lds + (bufoff) + ldsw + _i * 8192), 16, 0, 0); } while (0)
; #define PG8_LDA(dst, b, h) do { _Pragma("unroll") for (int m = 0; m < 4; ++m) _Pragma("unroll") for (int k = 0; k < 2; ++k) dst[m][k] = *(const PG8_LAS bf16x8*)(lds + PG8_SA(b, h) + aoff + m * 2048 + k * 1024); } while (0)
; #define PG8_LDB(dst, b, h) do { _Pragma("unroll") for (int n = 0; n < 2; ++n) _Pragma("unroll") for (int k = 0; k < 2; ++k) dst[n][k] = *(const PG8_LAS bf16x8*)(lds + PG8_SB(b, h) + boff + n * 2048 + k * 1024); } while (0)
; #define PG8_MMA(ai, bj, At, Bt) do { __builtin_amdgcn_s_setprio(1); _Pragma("unroll") for (int m = 0; m < 4; ++m) _Pragma("unroll") for (int n = 0; n < 2; ++n) _Pragma("unroll") for (int k = 0; k < 2; ++k) \
;         acc[ai][bj][m][n] = __builtin_amdgcn_mfma_f32_16x16x32_bf16(Bt[n][k], At[m][k], acc[ai][bj][m][n], 0, 0, 0); __builtin_amdgcn_s_setprio(0); } while (0)
; #define PG8_WAIT_V(n) asm volatile("s_waitcnt vmcnt(" #n ")" ::: "memory")
; #define PG8_WAIT_L(n) asm volatile("s_waitcnt lgkmcnt(" #n ")" ::: "memory")
; template <class Epi, class Sched, bool ALIGN_EPI = false, bool SP2 = false>
; __device__ __forceinline__ void gemm_phase(PG8_LAS unsigned char* lds, const Gemm g, const Sched& S, const Epi& E, const int tid) {
;     ...
;             const bool last = (t == nt - 2);
;             const char* a1 = cA + (size_t)(t + 1) * kstep;
;             const char* a2 = last ? nA : cA + (size_t)(t + 2) * kstep; const char* b2 = last ? nB : cB + (size_t)(t + 2) * kstep;
;             const char* a3 = a2 + kstep; const char* b3 = b2 + kstep;
;             if (last && has_next) S.a_ready(nxt);
;             if constexpr (SP2) {
;             PG8_LDB(B0, 0, 0); PG8_LDB(B1, 0, 1); PG8_SCHED; PG8_LDA(At, 0, 0); PG8_STAGE(PG8_SA(1, 1), a1 + hstep, voffA);
;             PG8_WAIT_V(8); PG8_WAIT_L(0); PG8_BAR; PG8_MMA(0, 0, At, B0); PG8_MMA(0, 1, At, B1); PG8_BAR; PG8_SCHED;
;             PG8_LDA(At, 0, 1); PG8_STAGE(PG8_SB(0, 0), b2, voffB); PG8_STAGE(PG8_SB(0, 1), b2 + hstep, voffB); PG8_STAGE(PG8_SA(0, 0), a2, voffA);
;             PG8_WAIT_V(8); PG8_WAIT_L(0); PG8_BAR; PG8_MMA(1, 0, At, B0); PG8_MMA(1, 1, At, B1); PG8_BAR; PG8_SCHED;
.LBB0_403:
	s_add_u32 s52, s50, 0x100
	s_addc_u32 s53, s51, 0
	s_add_i32 s76, 0, 0x10000
	s_cmpk_eq_i32 s75, 0x54
	s_cselect_b32 s57, s45, s53
	s_cselect_b32 s56, s44, s52
	s_cselect_b32 s55, s47, s73
	s_cselect_b32 s54, s46, s72
	s_add_i32 s77, 0, 0x14000
	v_add_u32_e32 v146, s76, v233
	v_add_u32_e32 v162, s77, v233
	ds_read_b128 v[126:129], v146
	ds_read_b128 v[130:133], v146 offset:1024
	ds_read_b128 v[142:145], v146 offset:2048
	ds_read_b128 v[146:149], v146 offset:3072
	ds_read_b128 v[150:153], v162
	ds_read_b128 v[154:157], v162 offset:1024
	ds_read_b128 v[158:161], v162 offset:2048
	ds_read_b128 v[162:165], v162 offset:3072
	v_lshl_add_u64 v[210:211], s[50:51], 0, v[192:193]
	s_add_i32 m0, s60, 0xc000
	ds_read_b128 v[166:169], v236
	ds_read_b128 v[170:173], v236 offset:1024
	ds_read_b128 v[174:177], v236 offset:2048
	ds_read_b128 v[178:181], v236 offset:3072
	ds_read_b128 v[194:197], v236 offset:4096
	ds_read_b128 v[198:201], v236 offset:5120
	ds_read_b128 v[202:205], v236 offset:6144
	ds_read_b128 v[206:209], v236 offset:7168
	global_load_lds_dwordx4 v[210:211], off
	v_lshl_add_u64 v[210:211], s[50:51], 0, v[190:191]
	s_add_i32 m0, s60, 0xe000
	s_nop 0
	global_load_lds_dwordx4 v[210:211], off
	s_waitcnt vmcnt(8)
	s_waitcnt lgkmcnt(0)
	s_barrier
	s_setprio 1
	v_mfma_f32_16x16x32_bf16 v[138:141], v[126:129], v[166:169], v[138:141]
	v_mfma_f32_16x16x32_bf16 v[134:137], v[142:145], v[166:169], v[134:137]
	v_mfma_f32_16x16x32_bf16 v[114:117], v[126:129], v[174:177], v[114:117]
	v_mfma_f32_16x16x32_bf16 v[110:113], v[142:145], v[174:177], v[110:113]
	v_mfma_f32_16x16x32_bf16 v[92:95], v[126:129], v[194:197], v[92:95]
	v_mfma_f32_16x16x32_bf16 v[88:91], v[142:145], v[194:197], v[88:91]
	v_mfma_f32_16x16x32_bf16 v[76:79], v[126:129], v[202:205], v[76:79]
	v_mfma_f32_16x16x32_bf16 v[72:75], v[142:145], v[202:205], v[72:75]
	v_mfma_f32_16x16x32_bf16 v[138:141], v[130:133], v[170:173], v[138:141]
	v_mfma_f32_16x16x32_bf16 v[134:137], v[146:149], v[170:173], v[134:137]
	v_mfma_f32_16x16x32_bf16 v[114:117], v[130:133], v[178:181], v[114:117]
	v_mfma_f32_16x16x32_bf16 v[110:113], v[146:149], v[178:181], v[110:113]
	v_mfma_f32_16x16x32_bf16 v[92:95], v[130:133], v[198:201], v[92:95]
	v_mfma_f32_16x16x32_bf16 v[88:91], v[146:149], v[198:201], v[88:91]
	v_mfma_f32_16x16x32_bf16 v[76:79], v[130:133], v[206:209], v[76:79]
	v_mfma_f32_16x16x32_bf16 v[72:75], v[146:149], v[206:209], v[72:75]
	v_mfma_f32_16x16x32_bf16 v[122:125], v[150:153], v[166:169], v[122:125]
	v_mfma_f32_16x16x32_bf16 v[118:121], v[158:161], v[166:169], v[118:121]
	v_mfma_f32_16x16x32_bf16 v[106:109], v[150:153], v[174:177], v[106:109]
	v_mfma_f32_16x16x32_bf16 v[102:105], v[158:161], v[174:177], v[102:105]
	v_mfma_f32_16x16x32_bf16 v[84:87], v[150:153], v[194:197], v[84:87]
	v_mfma_f32_16x16x32_bf16 v[80:83], v[158:161], v[194:197], v[80:83]
	v_mfma_f32_16x16x32_bf16 v[68:71], v[150:153], v[202:205], v[68:71]
	v_mfma_f32_16x16x32_bf16 v[64:67], v[158:161], v[202:205], v[64:67]
	v_mfma_f32_16x16x32_bf16 v[122:125], v[154:157], v[170:173], v[122:125]
	v_mfma_f32_16x16x32_bf16 v[118:121], v[162:165], v[170:173], v[118:121]
	v_mfma_f32_16x16x32_bf16 v[106:109], v[154:157], v[178:181], v[106:109]
	v_mfma_f32_16x16x32_bf16 v[102:105], v[162:165], v[178:181], v[102:105]
	v_mfma_f32_16x16x32_bf16 v[84:87], v[154:157], v[198:201], v[84:87]
	v_mfma_f32_16x16x32_bf16 v[80:83], v[162:165], v[198:201], v[80:83]
	v_mfma_f32_16x16x32_bf16 v[68:71], v[154:157], v[206:209], v[68:71]
	v_mfma_f32_16x16x32_bf16 v[64:67], v[162:165], v[206:209], v[64:67]
	s_setprio 0
	s_barrier
	s_add_i32 s50, s76, s59
	v_lshl_add_u64 v[210:211], s[54:55], 0, v[96:97]
	s_mov_b32 m0, s50
	ds_read_b128 v[166:169], v236 offset:16384
	ds_read_b128 v[170:173], v236 offset:17408
	ds_read_b128 v[174:177], v236 offset:18432
	ds_read_b128 v[178:181], v236 offset:19456
	ds_read_b128 v[194:197], v236 offset:20480
	ds_read_b128 v[198:201], v236 offset:21504
	ds_read_b128 v[202:205], v236 offset:22528
	ds_read_b128 v[206:209], v236 offset:23552
	global_load_lds_dwordx4 v[210:211], off
	s_add_i32 m0, s50, 0x2000
	s_add_u32 s50, s54, 0x160000
	v_lshl_add_u64 v[212:213], s[54:55], 0, v[98:99]
	s_addc_u32 s51, s55, 0
	s_add_i32 s76, s77, s59
	global_load_lds_dwordx4 v[212:213], off
	v_lshl_add_u64 v[214:215], s[50:51], 0, v[96:97]
	s_mov_b32 m0, s76
	v_lshl_add_u64 v[216:217], s[56:57], 0, v[186:187]
	global_load_lds_dwordx4 v[214:215], off
	v_lshl_add_u64 v[214:215], s[50:51], 0, v[98:99]
	s_add_i32 m0, s76, 0x2000
	s_nop 0
	global_load_lds_dwordx4 v[214:215], off
	v_lshl_add_u64 v[214:215], s[56:57], 0, v[188:189]
	s_mov_b32 m0, s60
	s_nop 0
	global_load_lds_dwordx4 v[214:215], off
	s_mov_b32 m0, s61
	s_nop 0
	global_load_lds_dwordx4 v[216:217], off
	s_waitcnt vmcnt(8)
	s_waitcnt lgkmcnt(0)
	s_barrier
; #define PG8_STAGE(bufoff, gbase, voff) do { _Pragma("unroll") for (int _i = 0; _i < 2; ++_i) \
;         __builtin_amdgcn_global_load_lds((const unsigned*)((const char*)(gbase) + (voff)[_i]), (PG8_LAS unsigned*)(lds + (bufoff) + ldsw + _i * 8192), 16, 0, 0); } while (0)
; #define PG8_LDA(dst, b, h) do { _Pragma("unroll") for (int m = 0; m < 4; ++m) _Pragma("unroll") for (int k = 0; k < 2; ++k) dst[m][k] = *(const PG8_LAS bf16x8*)(lds + PG8_SA(b, h) + aoff + m * 2048 + k * 1024); } while (0)
; #define PG8_LDB(dst, b, h) do { _Pragma("unroll") for (int n = 0; n < 2; ++n) _Pragma("unroll") for (int k = 0; k < 2; ++k) dst[n][k] = *(const PG8_LAS bf16x8*)(lds + PG8_SB(b, h) + boff + n * 2048 + k * 1024); } while (0)
; #define PG8_MMA(ai, bj, At, Bt) do { __builtin_amdgcn_s_setprio(1); _Pragma("unroll") for (int m = 0; m < 4; ++m) _Pragma("unroll") for (int n = 0; n < 2; ++n) _Pragma("unroll") for (int k = 0; k < 2; ++k) \
;         acc[ai][bj][m][n] = __builtin_amdgcn_mfma_f32_16x16x32_bf16(Bt[n][k], At[m][k], acc[ai][bj][m][n], 0, 0, 0); __builtin_amdgcn_s_setprio(0); } while (0)
; #define PG8_WAIT_V(n) asm volatile("s_waitcnt vmcnt(" #n ")" ::: "memory")
; #define PG8_WAIT_L(n) asm volatile("s_waitcnt lgkmcnt(" #n ")" ::: "memory")
; #define PG8_BAR __builtin_amdgcn_s_barrier()
; #define PG8_SCHED __builtin_amdgcn_sched_barrier(0)
; template <class Epi, class Sched, bool ALIGN_EPI = false, bool SP2 = false>
; __device__ __forceinline__ void gemm_phase(PG8_LAS unsigned char* lds, const Gemm g, const Sched& S, const Epi& E, const int tid) {
;     ...
;             PG8_WAIT_V(8); PG8_WAIT_L(0); PG8_BAR; PG8_MMA(1, 0, At, B0); PG8_MMA(1, 1, At, B1); PG8_BAR; PG8_SCHED;
;             PG8_LDB(B0, 1, 0); PG8_LDB(B1, 1, 1); PG8_SCHED; PG8_LDA(At, 1, 0); PG8_STAGE(PG8_SA(0, 1), a2 + hstep, voffA);
;             PG8_WAIT_V(8); PG8_WAIT_L(0); PG8_BAR; PG8_MMA(0, 0, At, B0); PG8_MMA(0, 1, At, B1); PG8_BAR; PG8_SCHED;
	s_setprio 1
	v_mfma_f32_16x16x32_bf16 v[60:63], v[126:129], v[166:169], v[60:63]
	v_mfma_f32_16x16x32_bf16 v[56:59], v[142:145], v[166:169], v[56:59]
	v_mfma_f32_16x16x32_bf16 v[44:47], v[126:129], v[174:177], v[44:47]
	v_mfma_f32_16x16x32_bf16 v[40:43], v[142:145], v[174:177], v[40:43]
	v_mfma_f32_16x16x32_bf16 v[28:31], v[126:129], v[194:197], v[28:31]
	v_mfma_f32_16x16x32_bf16 v[24:27], v[142:145], v[194:197], v[24:27]
	v_mfma_f32_16x16x32_bf16 v[12:15], v[126:129], v[202:205], v[12:15]
	v_mfma_f32_16x16x32_bf16 v[8:11], v[142:145], v[202:205], v[8:11]
	v_mfma_f32_16x16x32_bf16 v[60:63], v[130:133], v[170:173], v[60:63]
	v_mfma_f32_16x16x32_bf16 v[56:59], v[146:149], v[170:173], v[56:59]
	v_mfma_f32_16x16x32_bf16 v[44:47], v[130:133], v[178:181], v[44:47]
	v_mfma_f32_16x16x32_bf16 v[40:43], v[146:149], v[178:181], v[40:43]
	v_mfma_f32_16x16x32_bf16 v[28:31], v[130:133], v[198:201], v[28:31]
	v_mfma_f32_16x16x32_bf16 v[24:27], v[146:149], v[198:201], v[24:27]
	v_mfma_f32_16x16x32_bf16 v[12:15], v[130:133], v[206:209], v[12:15]
	v_mfma_f32_16x16x32_bf16 v[8:11], v[146:149], v[206:209], v[8:11]
	v_mfma_f32_16x16x32_bf16 v[52:55], v[150:153], v[166:169], v[52:55]
	v_mfma_f32_16x16x32_bf16 v[48:51], v[158:161], v[166:169], v[48:51]
	v_mfma_f32_16x16x32_bf16 v[36:39], v[150:153], v[174:177], v[36:39]
	v_mfma_f32_16x16x32_bf16 v[32:35], v[158:161], v[174:177], v[32:35]
	v_mfma_f32_16x16x32_bf16 v[20:23], v[150:153], v[194:197], v[20:23]
	v_mfma_f32_16x16x32_bf16 v[16:19], v[158:161], v[194:197], v[16:19]
	v_mfma_f32_16x16x32_bf16 v[4:7], v[150:153], v[202:205], v[4:7]
	v_mfma_f32_16x16x32_bf16 v[0:3], v[158:161], v[202:205], v[0:3]
	v_mfma_f32_16x16x32_bf16 v[52:55], v[154:157], v[170:173], v[52:55]
	v_mfma_f32_16x16x32_bf16 v[48:51], v[162:165], v[170:173], v[48:51]
	v_mfma_f32_16x16x32_bf16 v[36:39], v[154:157], v[178:181], v[36:39]
	v_mfma_f32_16x16x32_bf16 v[32:35], v[162:165], v[178:181], v[32:35]
	v_mfma_f32_16x16x32_bf16 v[20:23], v[154:157], v[198:201], v[20:23]
	v_mfma_f32_16x16x32_bf16 v[16:19], v[162:165], v[198:201], v[16:19]
	v_mfma_f32_16x16x32_bf16 v[4:7], v[154:157], v[206:209], v[4:7]
	v_mfma_f32_16x16x32_bf16 v[0:3], v[162:165], v[206:209], v[0:3]
	s_setprio 0
	s_barrier
	s_add_i32 s76, 0, 0x18000
	s_add_i32 s77, 0, 0x1c000
	v_add_u32_e32 v146, s76, v233
	v_add_u32_e32 v162, s77, v233
	ds_read_b128 v[126:129], v146
	ds_read_b128 v[130:133], v146 offset:1024
	ds_read_b128 v[142:145], v146 offset:2048
	ds_read_b128 v[146:149], v146 offset:3072
	ds_read_b128 v[150:153], v162
	ds_read_b128 v[154:157], v162 offset:1024
	ds_read_b128 v[158:161], v162 offset:2048
	ds_read_b128 v[162:165], v162 offset:3072
	s_add_u32 s50, s56, 0x160000
	s_addc_u32 s51, s57, 0
	s_mov_b32 m0, s64
	v_lshl_add_u64 v[218:219], s[50:51], 0, v[188:189]
	ds_read_b128 v[166:169], v236 offset:32768
	ds_read_b128 v[170:173], v236 offset:33792
	ds_read_b128 v[174:177], v236 offset:34816
	ds_read_b128 v[178:181], v236 offset:35840
	ds_read_b128 v[194:197], v236 offset:36864
	ds_read_b128 v[198:201], v236 offset:37888
	ds_read_b128 v[202:205], v236 offset:38912
	ds_read_b128 v[206:209], v236 offset:39936
	global_load_lds_dwordx4 v[218:219], off
	v_lshl_add_u64 v[218:219], s[50:51], 0, v[186:187]
	s_mov_b32 m0, s65
	s_nop 0
	global_load_lds_dwordx4 v[218:219], off
	s_waitcnt vmcnt(8)
	s_waitcnt lgkmcnt(0)
	s_barrier
	s_setprio 1
	v_mfma_f32_16x16x32_bf16 v[138:141], v[126:129], v[166:169], v[138:141]
	v_mfma_f32_16x16x32_bf16 v[134:137], v[142:145], v[166:169], v[134:137]
	v_mfma_f32_16x16x32_bf16 v[114:117], v[126:129], v[174:177], v[114:117]
	v_mfma_f32_16x16x32_bf16 v[110:113], v[142:145], v[174:177], v[110:113]
	v_mfma_f32_16x16x32_bf16 v[92:95], v[126:129], v[194:197], v[92:95]
	v_mfma_f32_16x16x32_bf16 v[88:91], v[142:145], v[194:197], v[88:91]
	v_mfma_f32_16x16x32_bf16 v[76:79], v[126:129], v[202:205], v[76:79]
	v_mfma_f32_16x16x32_bf16 v[72:75], v[142:145], v[202:205], v[72:75]
	v_mfma_f32_16x16x32_bf16 v[138:141], v[130:133], v[170:173], v[138:141]
	v_mfma_f32_16x16x32_bf16 v[134:137], v[146:149], v[170:173], v[134:137]
	v_mfma_f32_16x16x32_bf16 v[114:117], v[130:133], v[178:181], v[114:117]
	v_mfma_f32_16x16x32_bf16 v[110:113], v[146:149], v[178:181], v[110:113]
	v_mfma_f32_16x16x32_bf16 v[92:95], v[130:133], v[198:201], v[92:95]
	v_mfma_f32_16x16x32_bf16 v[88:91], v[146:149], v[198:201], v[88:91]
	v_mfma_f32_16x16x32_bf16 v[76:79], v[130:133], v[206:209], v[76:79]
	v_mfma_f32_16x16x32_bf16 v[72:75], v[146:149], v[206:209], v[72:75]
	v_mfma_f32_16x16x32_bf16 v[122:125], v[150:153], v[166:169], v[122:125]
	v_mfma_f32_16x16x32_bf16 v[118:121], v[158:161], v[166:169], v[118:121]
	v_mfma_f32_16x16x32_bf16 v[106:109], v[150:153], v[174:177], v[106:109]
	v_mfma_f32_16x16x32_bf16 v[102:105], v[158:161], v[174:177], v[102:105]
	v_mfma_f32_16x16x32_bf16 v[84:87], v[150:153], v[194:197], v[84:87]
	v_mfma_f32_16x16x32_bf16 v[80:83], v[158:161], v[194:197], v[80:83]
	v_mfma_f32_16x16x32_bf16 v[68:71], v[150:153], v[202:205], v[68:71]
	v_mfma_f32_16x16x32_bf16 v[64:67], v[158:161], v[202:205], v[64:67]
	v_mfma_f32_16x16x32_bf16 v[122:125], v[154:157], v[170:173], v[122:125]
	v_mfma_f32_16x16x32_bf16 v[118:121], v[162:165], v[170:173], v[118:121]
	v_mfma_f32_16x16x32_bf16 v[106:109], v[154:157], v[178:181], v[106:109]
	v_mfma_f32_16x16x32_bf16 v[102:105], v[162:165], v[178:181], v[102:105]
	v_mfma_f32_16x16x32_bf16 v[84:87], v[154:157], v[198:201], v[84:87]
	v_mfma_f32_16x16x32_bf16 v[80:83], v[162:165], v[198:201], v[80:83]
	v_mfma_f32_16x16x32_bf16 v[68:71], v[154:157], v[206:209], v[68:71]
	v_mfma_f32_16x16x32_bf16 v[64:67], v[162:165], v[206:209], v[64:67]
	s_setprio 0
	s_barrier
; #define PG8_GAS __attribute__((address_space(1)))
; #define PG8_STAGE(bufoff, gbase, voff) do { _Pragma("unroll") for (int _i = 0; _i < 2; ++_i) \
;         __builtin_amdgcn_global_load_lds((const unsigned*)((const char*)(gbase) + (voff)[_i]), (PG8_LAS unsigned*)(lds + (bufoff) + ldsw + _i * 8192), 16, 0, 0); } while (0)
; #define PG8_LDA(dst, b, h) do { _Pragma("unroll") for (int m = 0; m < 4; ++m) _Pragma("unroll") for (int k = 0; k < 2; ++k) dst[m][k] = *(const PG8_LAS bf16x8*)(lds + PG8_SA(b, h) + aoff + m * 2048 + k * 1024); } while (0)
; #define PG8_MMA(ai, bj, At, Bt) do { __builtin_amdgcn_s_setprio(1); _Pragma("unroll") for (int m = 0; m < 4; ++m) _Pragma("unroll") for (int n = 0; n < 2; ++n) _Pragma("unroll") for (int k = 0; k < 2; ++k) \
;         acc[ai][bj][m][n] = __builtin_amdgcn_mfma_f32_16x16x32_bf16(Bt[n][k], At[m][k], acc[ai][bj][m][n], 0, 0, 0); __builtin_amdgcn_s_setprio(0); } while (0)
; #define PG8_WAIT_V(n) asm volatile("s_waitcnt vmcnt(" #n ")" ::: "memory")
; #define PG8_WAIT_L(n) asm volatile("s_waitcnt lgkmcnt(" #n ")" ::: "memory")
; #define PG8_BAR __builtin_amdgcn_s_barrier()
;     __device__ __forceinline__ void operator()(const f32x4 (&acc)[2][2][4][2], const Unit& u, int wr, int wc, int fr, int fq) const {
;         const int row0 = u.pm * BM + wr * 64 + fr, col0 = u.pn * BM + wc * 32 + 8 * fq, lcol = u.pn * BM + (wc * 4 + fq) * 16;
; #pragma unroll
;         for (int ai = 0; ai < 2; ++ai) {
;             u32x4 L4[4], H4[4][2];
; #pragma unroll
;             for (int m = 0; m < 4; ++m) {
;                 const int row = row0 + ai * HALF + m * 16; const size_t off = (size_t)row * 2048 + col0, loff = (size_t)row * 2048 + lcol;
;                 L4[m] = *(const PG8_GAS u32x4*)(lin + loff); H4[m][0] = *(const PG8_GAS u32x4*)(hin + off); H4[m][1] = *(const PG8_GAS u32x4*)(hin + off + HALF);
;             }
; template <class Epi, class Sched, bool ALIGN_EPI = false, bool SP2 = false>
; __device__ __forceinline__ void gemm_phase(PG8_LAS unsigned char* lds, const Gemm g, const Sched& S, const Epi& E, const int tid) {
;     ...
;             PG8_LDA(At, 1, 1); PG8_STAGE(PG8_SB(1, 0), b3, voffB); PG8_STAGE(PG8_SB(1, 1), b3 + hstep, voffB); PG8_STAGE(PG8_SA(1, 0), a3, voffA);
;             PG8_WAIT_V(8); PG8_WAIT_L(0); PG8_BAR; PG8_MMA(1, 0, At, B0); PG8_MMA(1, 1, At, B1); PG8_BAR; PG8_SCHED;
	s_add_i32 s50, s76, s59
	v_lshl_add_u64 v[210:211], v[210:211], 0, s[28:29]
	s_mov_b32 m0, s50
	ds_read_b128 v[166:169], v236 offset:49152
	ds_read_b128 v[170:173], v236 offset:50176
	ds_read_b128 v[174:177], v236 offset:51200
	ds_read_b128 v[178:181], v236 offset:52224
	ds_read_b128 v[194:197], v236 offset:53248
	ds_read_b128 v[198:201], v236 offset:54272
	ds_read_b128 v[202:205], v236 offset:55296
	ds_read_b128 v[206:209], v236 offset:56320
	global_load_lds_dwordx4 v[210:211], off
	s_add_i32 m0, s50, 0x2000
	s_add_u32 s50, s54, 0x160080
	v_lshl_add_u64 v[210:211], v[212:213], 0, s[28:29]
	s_addc_u32 s51, s55, 0
	s_add_i32 s54, s77, s59
	global_load_lds_dwordx4 v[210:211], off
	v_lshl_add_u64 v[210:211], s[50:51], 0, v[96:97]
	s_mov_b32 m0, s54
	s_nop 0
	global_load_lds_dwordx4 v[210:211], off
	v_lshl_add_u64 v[210:211], s[50:51], 0, v[98:99]
	s_add_i32 m0, s54, 0x2000
	s_nop 0
	global_load_lds_dwordx4 v[210:211], off
	v_lshl_add_u64 v[210:211], v[214:215], 0, s[28:29]
	s_mov_b32 m0, s63
	s_nop 0
	global_load_lds_dwordx4 v[210:211], off
	v_lshl_add_u64 v[210:211], v[216:217], 0, s[28:29]
	s_mov_b32 m0, s66
	s_nop 0
	global_load_lds_dwordx4 v[210:211], off
	s_waitcnt vmcnt(8)
	s_waitcnt lgkmcnt(0)
	s_barrier
	s_setprio 1
	v_mfma_f32_16x16x32_bf16 v[60:63], v[126:129], v[166:169], v[60:63]
	v_mfma_f32_16x16x32_bf16 v[56:59], v[142:145], v[166:169], v[56:59]
	v_mfma_f32_16x16x32_bf16 v[44:47], v[126:129], v[174:177], v[44:47]
	v_mfma_f32_16x16x32_bf16 v[40:43], v[142:145], v[174:177], v[40:43]
	v_mfma_f32_16x16x32_bf16 v[28:31], v[126:129], v[194:197], v[28:31]
	v_mfma_f32_16x16x32_bf16 v[24:27], v[142:145], v[194:197], v[24:27]
	v_mfma_f32_16x16x32_bf16 v[12:15], v[126:129], v[202:205], v[12:15]
	v_mfma_f32_16x16x32_bf16 v[8:11], v[142:145], v[202:205], v[8:11]
	v_mfma_f32_16x16x32_bf16 v[60:63], v[130:133], v[170:173], v[60:63]
	v_mfma_f32_16x16x32_bf16 v[56:59], v[146:149], v[170:173], v[56:59]
	v_mfma_f32_16x16x32_bf16 v[44:47], v[130:133], v[178:181], v[44:47]
	v_mfma_f32_16x16x32_bf16 v[40:43], v[146:149], v[178:181], v[40:43]
	v_mfma_f32_16x16x32_bf16 v[28:31], v[130:133], v[198:201], v[28:31]
	v_mfma_f32_16x16x32_bf16 v[24:27], v[146:149], v[198:201], v[24:27]
	v_mfma_f32_16x16x32_bf16 v[12:15], v[130:133], v[206:209], v[12:15]
	v_mfma_f32_16x16x32_bf16 v[8:11], v[146:149], v[206:209], v[8:11]
	v_mfma_f32_16x16x32_bf16 v[52:55], v[150:153], v[166:169], v[52:55]
	v_mfma_f32_16x16x32_bf16 v[48:51], v[158:161], v[166:169], v[48:51]
	v_mfma_f32_16x16x32_bf16 v[36:39], v[150:153], v[174:177], v[36:39]
	v_mfma_f32_16x16x32_bf16 v[32:35], v[158:161], v[174:177], v[32:35]
	v_mfma_f32_16x16x32_bf16 v[20:23], v[150:153], v[194:197], v[20:23]
	v_mfma_f32_16x16x32_bf16 v[16:19], v[158:161], v[194:197], v[16:19]
	v_mfma_f32_16x16x32_bf16 v[4:7], v[150:153], v[202:205], v[4:7]
	v_mfma_f32_16x16x32_bf16 v[0:3], v[158:161], v[202:205], v[0:3]
	v_mfma_f32_16x16x32_bf16 v[52:55], v[154:157], v[170:173], v[52:55]
	v_mfma_f32_16x16x32_bf16 v[48:51], v[162:165], v[170:173], v[48:51]
	v_mfma_f32_16x16x32_bf16 v[36:39], v[154:157], v[178:181], v[36:39]
	v_mfma_f32_16x16x32_bf16 v[32:35], v[162:165], v[178:181], v[32:35]
	v_mfma_f32_16x16x32_bf16 v[20:23], v[154:157], v[198:201], v[20:23]
	v_mfma_f32_16x16x32_bf16 v[16:19], v[162:165], v[198:201], v[16:19]
	v_mfma_f32_16x16x32_bf16 v[4:7], v[154:157], v[206:209], v[4:7]
	v_mfma_f32_16x16x32_bf16 v[0:3], v[162:165], v[206:209], v[0:3]
	s_setprio 0
	s_barrier
	s_add_i32 s75, s75, 2
	s_add_u32 s72, s72, 0x100
	s_addc_u32 s73, s73, 0
	s_cmpk_gt_u32 s75, 0x55
	s_mov_b64 s[50:51], s[52:53]
	s_cbranch_scc0 .LBB0_403
	v_and_b32_e32 v127, 64, v228
	v_xor_b32_e32 v126, 16, v228
	v_add_u32_e32 v127, 64, v127
	v_cmp_lt_i32_e32 vcc, v126, v127
	s_lshl_b32 s50, s70, 8
	v_lshl_add_u32 v198, s71, 8, v101
	v_cndmask_b32_e32 v126, v228, v126, vcc
	v_or_b32_e32 v194, s50, v235
	v_lshlrev_b32_e32 v238, 2, v126
	v_xor_b32_e32 v126, 32, v228
	v_or_b32_e32 v196, s50, v234
	v_ashrrev_i32_e32 v195, 31, v194
	v_cmp_lt_i32_e32 vcc, v126, v127
	v_ashrrev_i32_e32 v199, 31, v198
	v_ashrrev_i32_e32 v197, 31, v196
	v_cndmask_b32_e32 v126, v228, v126, vcc
	v_lshl_add_u64 v[202:203], s[34:35], 0, v[194:195]
	v_lshlrev_b64 v[216:217], 11, v[198:199]
	v_lshlrev_b32_e32 v237, 2, v126
	v_lshlrev_b64 v[218:219], 1, v[196:197]
	v_lshl_add_u64 v[126:127], v[202:203], 0, v[216:217]
	v_lshl_add_u64 v[200:201], s[30:31], 0, v[218:219]
	global_load_dwordx4 v[170:173], v[126:127], off
	v_lshlrev_b64 v[220:221], 12, v[198:199]
	v_lshl_add_u64 v[126:127], v[200:201], 0, v[220:221]
	global_load_dwordx4 v[178:181], v[126:127], off
	global_load_dwordx4 v[174:177], v[126:127], off offset:256
	v_or_b32_e32 v212, 16, v198
	v_ashrrev_i32_e32 v213, 31, v212
	v_lshlrev_b64 v[214:215], 11, v[212:213]
	v_lshl_add_u64 v[126:127], v[202:203], 0, v[214:215]
	v_or_b32_e32 v208, 32, v198
	global_load_dwordx4 v[158:161], v[126:127], off
	v_lshlrev_b64 v[126:127], 12, v[212:213]
	v_ashrrev_i32_e32 v209, 31, v208
	v_lshl_add_u64 v[126:127], v[200:201], 0, v[126:127]
	v_lshlrev_b64 v[210:211], 11, v[208:209]
	global_load_dwordx4 v[166:169], v[126:127], off
	global_load_dwordx4 v[162:165], v[126:127], off offset:256
	v_lshl_add_u64 v[126:127], v[202:203], 0, v[210:211]
	v_or_b32_e32 v204, 48, v198
	global_load_dwordx4 v[146:149], v[126:127], off
	v_lshlrev_b64 v[126:127], 12, v[208:209]
	v_ashrrev_i32_e32 v205, 31, v204
	v_lshl_add_u64 v[126:127], v[200:201], 0, v[126:127]
	v_lshlrev_b64 v[206:207], 11, v[204:205]
	v_lshlrev_b64 v[130:131], 12, v[204:205]
	global_load_dwordx4 v[154:157], v[126:127], off
	global_load_dwordx4 v[150:153], v[126:127], off offset:256
	v_lshl_add_u64 v[126:127], v[202:203], 0, v[206:207]
	v_lshl_add_u64 v[130:131], v[200:201], 0, v[130:131]
	global_load_dwordx4 v[126:129], v[126:127], off
	s_nop 0
	global_load_dwordx4 v[142:145], v[130:131], off
	s_nop 0
	global_load_dwordx4 v[130:133], v[130:131], off offset:256
	v_mov_b32_e32 v243, v136
	v_mov_b32_e32 v242, v140
	s_waitcnt vmcnt(0)
; #define PG8_GAS __attribute__((address_space(1)))
; __device__ __forceinline__ float e_x24(unsigned h16, unsigned l8) { return __uint_as_float(((h16 - (l8 >> 7)) << 16) | (l8 << 8)); }
;     __device__ __forceinline__ void operator()(const f32x4 (&acc)[2][2][4][2], const Unit& u, int wr, int wc, int fr, int fq) const {
;     ...
;             for (int m = 0; m < 4; ++m) {
;                 const int row = row0 + ai * HALF + m * 16; const size_t off = (size_t)row * 2048 + col0, loff = (size_t)row * 2048 + lcol; float ss = 0.f;
;                 const u32x4 l4 = L4[m];
;                 u32x4 lo4;
; #pragma unroll
;                 for (int bj = 0; bj < 2; ++bj) {
;                     const u32x4 h4 = H4[m][bj];
;                     u32x4 ho;
; #pragma unroll
;                     for (int j = 0; j < 4; ++j) {
;                         const unsigned lw = l4[2 * bj + (j >> 1)], lb0 = (lw >> (16 * (j & 1))) & 0xffu, lb1 = (lw >> (16 * (j & 1) + 8)) & 0xffu;
;                         const float x0 = e_x24(h4[j] & 0xffffu, lb0) + acc[ai][bj][m][j >> 1][2 * (j & 1)] * scale, x1 = e_x24(h4[j] >> 16, lb1) + acc[ai][bj][m][j >> 1][2 * (j & 1) + 1] * scale;
;                         const unsigned b0 = __float_as_uint(x0), b1 = __float_as_uint(x1);
;                         ho[j] = ((b0 + 0x8000u) >> 16) | ((b1 + 0x8000u) & 0xffff0000u);
;                         const unsigned nb = ((b0 >> 8) & 0xffu) | (b1 & 0xff00u);
;                         if ((j & 1) == 0) lo4[2 * bj + (j >> 1)] = nb; else lo4[2 * bj + (j >> 1)] |= nb << 16;
;                         ss += x0 * x0 + x1 * x1;
;                     }
;                     *(PG8_GAS u32x4*)(hout + off + bj * HALF) = ho;
	v_lshrrev_b32_sdwa v222, v229, v171 dst_sel:DWORD dst_unused:UNUSED_PAD src0_sel:DWORD src1_sel:BYTE_0
	v_lshrrev_b32_sdwa v223, v229, v170 dst_sel:DWORD dst_unused:UNUSED_PAD src0_sel:DWORD src1_sel:BYTE_0
	v_sub_u32_sdwa v224, v178, v223 dst_sel:WORD_1 dst_unused:UNUSED_PAD src0_sel:DWORD src1_sel:DWORD
	v_sub_u32_sdwa v222, v180, v222 dst_sel:WORD_1 dst_unused:UNUSED_PAD src0_sel:DWORD src1_sel:DWORD
	v_lshlrev_b32_sdwa v223, v230, v171 dst_sel:DWORD dst_unused:UNUSED_PAD src0_sel:DWORD src1_sel:BYTE_0
	v_lshlrev_b32_sdwa v225, v230, v170 dst_sel:DWORD dst_unused:UNUSED_PAD src0_sel:DWORD src1_sel:BYTE_0
	v_or_b32_e32 v223, v222, v223
	v_or_b32_e32 v222, v224, v225
	v_mov_b32_e32 v224, v138
	v_mov_b32_e32 v225, v134
	v_pk_fma_f32 v[222:223], v[224:225], 0.5, v[222:223] op_sel_hi:[1,0,1]
	v_lshlrev_b32_e32 v224, 1, v170
	v_add_u32_e32 v134, 0x8000, v222
	v_lshrrev_b32_e32 v138, 16, v134
	v_lshlrev_b32_e32 v134, 1, v171
	v_and_b32_e32 v134, 0x10000, v134
	v_and_b32_e32 v224, 0x10000, v224
	v_sub_u32_e32 v134, v180, v134
	v_sub_u32_e32 v178, v178, v224
	v_and_b32_e32 v134, 0xffff0000, v134
	v_and_b32_e32 v178, 0xffff0000, v178
	v_and_b32_e32 v180, 0xff00, v171
	v_and_b32_e32 v224, 0xff00, v170
	v_or_b32_e32 v225, v134, v180
	v_or_b32_e32 v224, v178, v224
	v_mov_b32_e32 v134, v139
	v_pk_fma_f32 v[224:225], v[134:135], 0.5, v[224:225] op_sel_hi:[1,0,1]
	v_and_b32_sdwa v135, v171, s93 dst_sel:DWORD dst_unused:UNUSED_PAD src0_sel:WORD_1 src1_sel:DWORD
	v_and_b32_sdwa v178, v170, s93 dst_sel:DWORD dst_unused:UNUSED_PAD src0_sel:WORD_1 src1_sel:DWORD
	v_lshlrev_b32_sdwa v239, v231, v170 dst_sel:DWORD dst_unused:UNUSED_PAD src0_sel:DWORD src1_sel:BYTE_3
	v_lshlrev_b32_sdwa v136, v231, v171 dst_sel:DWORD dst_unused:UNUSED_PAD src0_sel:DWORD src1_sel:BYTE_3
	v_lshrrev_b32_e32 v180, 7, v178
	v_lshrrev_b32_e32 v240, 7, v135
	v_and_b32_e32 v136, 0x10000, v136
	v_and_b32_e32 v140, 0x10000, v239
	v_sub_u32_sdwa v180, v179, v180 dst_sel:WORD_1 dst_unused:UNUSED_PAD src0_sel:DWORD src1_sel:DWORD
	v_sub_u32_sdwa v240, v181, v240 dst_sel:WORD_1 dst_unused:UNUSED_PAD src0_sel:DWORD src1_sel:DWORD
	v_lshlrev_b32_e32 v135, 8, v135
	v_lshlrev_b32_e32 v178, 8, v178
	v_sub_u32_e32 v136, v181, v136
	v_sub_u32_e32 v140, v179, v140
	v_or_b32_e32 v241, v240, v135
	v_or_b32_e32 v240, v180, v178
	v_and_b32_e32 v136, 0xffff0000, v136
	v_and_b32_e32 v140, 0xffff0000, v140
	v_lshlrev_b32_sdwa v171, v230, v171 dst_sel:DWORD dst_unused:UNUSED_PAD src0_sel:DWORD src1_sel:BYTE_3
	v_lshlrev_b32_sdwa v170, v230, v170 dst_sel:DWORD dst_unused:UNUSED_PAD src0_sel:DWORD src1_sel:BYTE_3
	v_pk_fma_f32 v[240:241], v[242:243], 0.5, v[240:241] op_sel_hi:[1,0,1]
	v_or_b32_e32 v171, v136, v171
	v_or_b32_e32 v170, v140, v170
	v_mov_b32_e32 v136, v141
	v_add_u32_e32 v135, 0x8000, v240
	v_pk_fma_f32 v[140:141], v[136:137], 0.5, v[170:171] op_sel_hi:[1,0,1]
	v_lshrrev_b32_e32 v135, 16, v135
	v_add_u32_e32 v136, 0x8000, v140
	v_and_or_b32 v135, v136, s90, v135
	v_pk_mul_f32 v[136:137], v[140:141], v[140:141]
	v_add_u32_e32 v178, 0x8000, v141
	v_pk_fma_f32 v[170:171], v[240:241], v[240:241], v[136:137]
	v_add_u32_e32 v136, 0x8000, v223
	v_lshrrev_b32_e32 v136, 16, v136
	v_add_u32_e32 v137, 0x8000, v225
	v_and_or_b32 v136, v137, s90, v136
	v_add_u32_e32 v137, 0x8000, v241
	v_lshrrev_b32_e32 v137, 16, v137
	v_add_u32_e32 v134, 0x8000, v224
	v_and_or_b32 v137, v178, s90, v137
	v_lshl_add_u64 v[178:179], s[30:31], 0, v[220:221]
	v_and_or_b32 v134, v134, s90, v138
	v_lshl_add_u64 v[178:179], v[178:179], 0, v[218:219]
	global_store_dwordx4 v[178:179], v[134:137], off
	v_lshlrev_b32_sdwa v220, v231, v172 dst_sel:DWORD dst_unused:UNUSED_PAD src0_sel:DWORD src1_sel:BYTE_3
	v_mov_b32_e32 v219, v120
	v_lshrrev_b32_sdwa v134, v229, v173 dst_sel:DWORD dst_unused:UNUSED_PAD src0_sel:DWORD src1_sel:BYTE_0
	v_lshrrev_b32_sdwa v135, v229, v172 dst_sel:DWORD dst_unused:UNUSED_PAD src0_sel:DWORD src1_sel:BYTE_0
	v_sub_u32_sdwa v136, v174, v135 dst_sel:WORD_1 dst_unused:UNUSED_PAD src0_sel:DWORD src1_sel:DWORD
	v_sub_u32_sdwa v134, v176, v134 dst_sel:WORD_1 dst_unused:UNUSED_PAD src0_sel:DWORD src1_sel:DWORD
	v_lshlrev_b32_sdwa v135, v230, v173 dst_sel:DWORD dst_unused:UNUSED_PAD src0_sel:DWORD src1_sel:BYTE_0
	v_lshlrev_b32_sdwa v137, v230, v172 dst_sel:DWORD dst_unused:UNUSED_PAD src0_sel:DWORD src1_sel:BYTE_0
	v_or_b32_e32 v135, v134, v135
	v_or_b32_e32 v134, v136, v137
	v_mov_b32_e32 v136, v122
	v_mov_b32_e32 v137, v118
	v_pk_fma_f32 v[134:135], v[136:137], 0.5, v[134:135] op_sel_hi:[1,0,1]
; #define PG8_GAS __attribute__((address_space(1)))
; __device__ __forceinline__ float e_x24(unsigned h16, unsigned l8) { return __uint_as_float(((h16 - (l8 >> 7)) << 16) | (l8 << 8)); }
;     __device__ __forceinline__ void operator()(const f32x4 (&acc)[2][2][4][2], const Unit& u, int wr, int wc, int fr, int fq) const {
;     ...
;                 for (int bj = 0; bj < 2; ++bj) {
;                     const u32x4 h4 = H4[m][bj];
;                     u32x4 ho;
; #pragma unroll
;                     for (int j = 0; j < 4; ++j) {
;                         const unsigned lw = l4[2 * bj + (j >> 1)], lb0 = (lw >> (16 * (j & 1))) & 0xffu, lb1 = (lw >> (16 * (j & 1) + 8)) & 0xffu;
;                         const float x0 = e_x24(h4[j] & 0xffffu, lb0) + acc[ai][bj][m][j >> 1][2 * (j & 1)] * scale, x1 = e_x24(h4[j] >> 16, lb1) + acc[ai][bj][m][j >> 1][2 * (j & 1) + 1] * scale;
;                         const unsigned b0 = __float_as_uint(x0), b1 = __float_as_uint(x1);
;                         ho[j] = ((b0 + 0x8000u) >> 16) | ((b1 + 0x8000u) & 0xffff0000u);
;                         const unsigned nb = ((b0 >> 8) & 0xffu) | (b1 & 0xff00u);
;                         if ((j & 1) == 0) lo4[2 * bj + (j >> 1)] = nb; else lo4[2 * bj + (j >> 1)] |= nb << 16;
;                         ss += x0 * x0 + x1 * x1;
;                     }
;                     *(PG8_GAS u32x4*)(hout + off + bj * HALF) = ho;
;                 }
;                 *(PG8_GAS u32x4*)(lout + loff) = lo4;
;                 ss += __shfl_xor(ss, 16); ss += __shfl_xor(ss, 32);
;                 if (fq == 0) __hip_atomic_fetch_add((PG8_GAS unsigned long long*)(rowsq_out + row), (unsigned long long)(ss * 16777216.0f + 0.5f), __ATOMIC_RELAXED, __HIP_MEMORY_SCOPE_AGENT);
	v_lshlrev_b32_e32 v122, 1, v172
	v_add_u32_e32 v118, 0x8000, v134
	v_lshrrev_b32_e32 v180, 16, v118
	v_lshlrev_b32_e32 v118, 1, v173
	v_and_b32_e32 v118, 0x10000, v118
	v_and_b32_e32 v122, 0x10000, v122
	v_sub_u32_e32 v118, v176, v118
	v_sub_u32_e32 v122, v174, v122
	v_and_b32_e32 v118, 0xffff0000, v118
	v_and_b32_e32 v122, 0xffff0000, v122
	v_and_b32_e32 v136, 0xff00, v173
	v_and_b32_e32 v174, 0xff00, v172
	v_or_b32_e32 v137, v118, v136
	v_or_b32_e32 v136, v122, v174
	v_mov_b32_e32 v118, v123
	v_pk_fma_f32 v[122:123], v[118:119], 0.5, v[136:137] op_sel_hi:[1,0,1]
	v_and_b32_sdwa v119, v173, s93 dst_sel:DWORD dst_unused:UNUSED_PAD src0_sel:WORD_1 src1_sel:DWORD
	v_add_u32_e32 v118, 0x8000, v122
	v_and_b32_sdwa v174, v172, s93 dst_sel:DWORD dst_unused:UNUSED_PAD src0_sel:WORD_1 src1_sel:DWORD
	v_lshlrev_b32_sdwa v120, v231, v173 dst_sel:DWORD dst_unused:UNUSED_PAD src0_sel:DWORD src1_sel:BYTE_3
	v_and_or_b32 v118, v118, s90, v180
	v_lshrrev_b32_e32 v176, 7, v174
	v_lshrrev_b32_e32 v180, 7, v119
	v_mov_b32_e32 v218, v124
	v_and_b32_e32 v120, 0x10000, v120
	v_and_b32_e32 v124, 0x10000, v220
	v_sub_u32_sdwa v176, v175, v176 dst_sel:WORD_1 dst_unused:UNUSED_PAD src0_sel:DWORD src1_sel:DWORD
	v_sub_u32_sdwa v180, v177, v180 dst_sel:WORD_1 dst_unused:UNUSED_PAD src0_sel:DWORD src1_sel:DWORD
	v_lshlrev_b32_e32 v119, 8, v119
	v_lshlrev_b32_e32 v174, 8, v174
	v_sub_u32_e32 v120, v177, v120
	v_sub_u32_e32 v124, v175, v124
	v_or_b32_e32 v181, v180, v119
	v_or_b32_e32 v180, v176, v174
	v_and_b32_e32 v120, 0xffff0000, v120
	v_and_b32_e32 v124, 0xffff0000, v124
	v_lshlrev_b32_sdwa v173, v230, v173 dst_sel:DWORD dst_unused:UNUSED_PAD src0_sel:DWORD src1_sel:BYTE_3
	v_lshlrev_b32_sdwa v172, v230, v172 dst_sel:DWORD dst_unused:UNUSED_PAD src0_sel:DWORD src1_sel:BYTE_3
	v_pk_fma_f32 v[180:181], v[218:219], 0.5, v[180:181] op_sel_hi:[1,0,1]
	v_or_b32_e32 v173, v120, v173
	v_or_b32_e32 v172, v124, v172
	v_mov_b32_e32 v120, v125
	v_add_u32_e32 v119, 0x8000, v180
	v_pk_fma_f32 v[124:125], v[120:121], 0.5, v[172:173] op_sel_hi:[1,0,1]
	v_lshrrev_b32_e32 v119, 16, v119
	v_add_u32_e32 v120, 0x8000, v124
	v_pk_mul_f32 v[138:139], v[224:225], v[224:225]
	v_pk_mul_f32 v[136:137], v[122:123], v[122:123]
	v_and_or_b32 v119, v120, s90, v119
	v_pk_mul_f32 v[120:121], v[124:125], v[124:125]
	v_pk_fma_f32 v[138:139], v[222:223], v[222:223], v[138:139]
	v_pk_fma_f32 v[136:137], v[134:135], v[134:135], v[136:137]
	v_pk_fma_f32 v[172:173], v[180:181], v[180:181], v[120:121]
	v_add_u32_e32 v120, 0x8000, v135
	v_lshrrev_b32_e32 v134, 8, v134
	v_lshrrev_b32_e32 v120, 16, v120
	v_add_u32_e32 v121, 0x8000, v123
	v_perm_b32 v122, v122, v134, s94
	v_add_f32_e32 v134, v138, v170
	v_and_or_b32 v120, v121, s90, v120
	v_add_u32_e32 v121, 0x8000, v181
	v_add_f32_e32 v134, v139, v134
	v_lshrrev_b32_e32 v121, 16, v121
	v_add_u32_e32 v174, 0x8000, v125
	v_add_f32_e32 v134, v171, v134
	v_and_or_b32 v121, v174, s90, v121
	v_lshrrev_b32_e32 v174, 8, v181
	v_lshrrev_b32_e32 v175, 8, v180
	v_add_f32_e32 v134, v136, v134
	v_lshrrev_b32_e32 v176, 8, v241
	v_lshrrev_b32_e32 v177, 8, v240
	v_perm_b32 v124, v124, v175, s94
	v_perm_b32 v125, v125, v174, s94
	v_lshrrev_b32_e32 v135, 8, v135
	v_lshrrev_b32_e32 v174, 8, v223
	v_lshrrev_b32_e32 v175, 8, v222
	v_add_f32_e32 v134, v172, v134
	v_perm_b32 v140, v140, v177, s94
	v_perm_b32 v141, v141, v176, s94
	v_perm_b32 v175, v224, v175, s94
	v_perm_b32 v174, v225, v174, s94
	v_perm_b32 v123, v123, v135, s94
	v_add_f32_e32 v134, v137, v134
	global_store_dwordx4 v[178:179], v[118:121], off offset:256
	v_lshl_or_b32 v125, v125, 16, v123
	v_lshl_or_b32 v124, v124, 16, v122
	v_lshl_add_u64 v[118:119], s[34:35], 0, v[216:217]
	v_lshl_or_b32 v123, v141, 16, v174
	v_lshl_or_b32 v122, v140, 16, v175
	v_add_f32_e32 v134, v173, v134
	v_lshl_add_u64 v[118:119], v[118:119], 0, v[194:195]
	global_store_dwordx4 v[118:119], v[122:125], off
	ds_bpermute_b32 v118, v238, v134
	s_waitcnt lgkmcnt(0)
	v_add_f32_e32 v118, v134, v118
	ds_bpermute_b32 v119, v237, v118
	s_and_saveexec_b64 s[50:51], s[40:41]
	s_cbranch_execz .LBB0_406
	s_waitcnt lgkmcnt(0)
	v_add_f32_e32 v118, v118, v119
	v_fma_f32 v118, v118, s80, 0.5
	v_trunc_f32_e32 v118, v118
	v_mul_f32_e32 v119, 0x2f800000, v118
	v_floor_f32_e32 v119, v119
	v_fmac_f32_e32 v118, 0xcf800000, v119
	v_cvt_u32_f32_e32 v118, v118
	v_cvt_u32_f32_e32 v119, v119
	v_lshl_add_u64 v[120:121], v[198:199], 3, s[48:49]
	global_atomic_add_x2 v[120:121], v[118:119], off

; #define PG8_STAGE(bufoff, gbase, voff) do { _Pragma("unroll") for (int _i = 0; _i < 2; ++_i) \
;         __builtin_amdgcn_global_load_lds((const unsigned*)((const char*)(gbase) + (voff)[_i]), (PG8_LAS unsigned*)(lds + (bufoff) + ldsw + _i * 8192), 16, 0, 0); } while (0)
; #define PG8_LDA(dst, b, h) do { _Pragma("unroll") for (int m = 0; m < 4; ++m) _Pragma("unroll") for (int k = 0; k < 2; ++k) dst[m][k] = *(const PG8_LAS bf16x8*)(lds + PG8_SA(b, h) + aoff + m * 2048 + k * 1024); } while (0)
; #define PG8_LDB(dst, b, h) do { _Pragma("unroll") for (int n = 0; n < 2; ++n) _Pragma("unroll") for (int k = 0; k < 2; ++k) dst[n][k] = *(const PG8_LAS bf16x8*)(lds + PG8_SB(b, h) + boff + n * 2048 + k * 1024); } while (0)
; #define PG8_MMA(ai, bj, At, Bt) do { __builtin_amdgcn_s_setprio(1); _Pragma("unroll") for (int m = 0; m < 4; ++m) _Pragma("unroll") for (int n = 0; n < 2; ++n) _Pragma("unroll") for (int k = 0; k < 2; ++k) \
;         acc[ai][bj][m][n] = __builtin_amdgcn_mfma_f32_16x16x32_bf16(Bt[n][k], At[m][k], acc[ai][bj][m][n], 0, 0, 0); __builtin_amdgcn_s_setprio(0); } while (0)
; #define PG8_WAIT_V(n) asm volatile("s_waitcnt vmcnt(" #n ")" ::: "memory")
; #define PG8_WAIT_L(n) asm volatile("s_waitcnt lgkmcnt(" #n ")" ::: "memory")
; template <class Epi, class Sched, bool ALIGN_EPI = false, bool SP2 = false>
; __device__ __forceinline__ void gemm_phase(PG8_LAS unsigned char* lds, const Gemm g, const Sched& S, const Epi& E, const int tid) {
;     ...
;             const bool last = (t == nt - 2);
;             const char* a1 = cA + (size_t)(t + 1) * kstep;
;             const char* a2 = last ? nA : cA + (size_t)(t + 2) * kstep; const char* b2 = last ? nB : cB + (size_t)(t + 2) * kstep;
;             const char* a3 = a2 + kstep; const char* b3 = b2 + kstep;
;             if (last && has_next) S.a_ready(nxt);
;             if constexpr (SP2) {
;             PG8_LDB(B0, 0, 0); PG8_LDB(B1, 0, 1); PG8_SCHED; PG8_LDA(At, 0, 0); PG8_STAGE(PG8_SA(1, 1), a1 + hstep, voffA);
;             PG8_WAIT_V(8); PG8_WAIT_L(0); PG8_BAR; PG8_MMA(0, 0, At, B0); PG8_MMA(0, 1, At, B1); PG8_BAR; PG8_SCHED;
;             PG8_LDA(At, 0, 1); PG8_STAGE(PG8_SB(0, 0), b2, voffB); PG8_STAGE(PG8_SB(0, 1), b2 + hstep, voffB); PG8_STAGE(PG8_SA(0, 0), a2, voffA);
;             PG8_WAIT_V(8); PG8_WAIT_L(0); PG8_BAR; PG8_MMA(1, 0, At, B0); PG8_MMA(1, 1, At, B1); PG8_BAR; PG8_SCHED;
.LBB0_488:
	s_add_u32 s58, s42, 0xfff80080
	s_addc_u32 s59, s43, -1
	s_add_i32 s78, 0, 0x10000
	s_cmp_eq_u32 s77, 28
	s_cselect_b32 s61, s53, s59
	s_cselect_b32 s60, s72, s58
	s_cselect_b32 s59, s51, s76
	s_cselect_b32 s58, s73, s75
	s_add_i32 s80, 0, 0x14000
	v_add_u32_e32 v156, s78, v163
	v_add_u32_e32 v160, s80, v163
	ds_read_b128 v[144:147], v156
	ds_read_b128 v[148:151], v156 offset:1024
	ds_read_b128 v[152:155], v156 offset:2048
	ds_read_b128 v[156:159], v156 offset:3072
	ds_read_b128 v[166:169], v160
	ds_read_b128 v[170:173], v160 offset:1024
	ds_read_b128 v[174:177], v160 offset:2048
	ds_read_b128 v[178:181], v160 offset:3072
	v_lshl_add_u64 v[160:161], s[42:43], 0, v[142:143]
	s_add_i32 m0, s63, 0xc000
	ds_read_b128 v[186:189], v165
	ds_read_b128 v[190:193], v165 offset:1024
	ds_read_b128 v[194:197], v165 offset:2048
	ds_read_b128 v[198:201], v165 offset:3072
	ds_read_b128 v[202:205], v165 offset:4096
	ds_read_b128 v[206:209], v165 offset:5120
	ds_read_b128 v[210:213], v165 offset:6144
	ds_read_b128 v[214:217], v165 offset:7168
	global_load_lds_dwordx4 v[160:161], off
	v_lshl_add_u64 v[160:161], s[42:43], 0, v[140:141]
	s_add_i32 m0, s63, 0xe000
	s_nop 0
	global_load_lds_dwordx4 v[160:161], off
	s_waitcnt vmcnt(8)
	s_waitcnt lgkmcnt(0)
	s_barrier
	s_setprio 1
	v_mfma_f32_16x16x32_bf16 v[122:125], v[144:147], v[186:189], v[122:125]
	v_mfma_f32_16x16x32_bf16 v[118:121], v[152:155], v[186:189], v[118:121]
	v_mfma_f32_16x16x32_bf16 v[110:113], v[144:147], v[194:197], v[110:113]
	v_mfma_f32_16x16x32_bf16 v[106:109], v[152:155], v[194:197], v[106:109]
	v_mfma_f32_16x16x32_bf16 v[88:91], v[144:147], v[202:205], v[88:91]
	v_mfma_f32_16x16x32_bf16 v[84:87], v[152:155], v[202:205], v[84:87]
	v_mfma_f32_16x16x32_bf16 v[72:75], v[144:147], v[210:213], v[72:75]
	v_mfma_f32_16x16x32_bf16 v[68:71], v[152:155], v[210:213], v[68:71]
	v_mfma_f32_16x16x32_bf16 v[122:125], v[148:151], v[190:193], v[122:125]
	v_mfma_f32_16x16x32_bf16 v[118:121], v[156:159], v[190:193], v[118:121]
	v_mfma_f32_16x16x32_bf16 v[110:113], v[148:151], v[198:201], v[110:113]
	v_mfma_f32_16x16x32_bf16 v[106:109], v[156:159], v[198:201], v[106:109]
	v_mfma_f32_16x16x32_bf16 v[88:91], v[148:151], v[206:209], v[88:91]
	v_mfma_f32_16x16x32_bf16 v[84:87], v[156:159], v[206:209], v[84:87]
	v_mfma_f32_16x16x32_bf16 v[72:75], v[148:151], v[214:217], v[72:75]
	v_mfma_f32_16x16x32_bf16 v[68:71], v[156:159], v[214:217], v[68:71]
	v_mfma_f32_16x16x32_bf16 v[130:133], v[166:169], v[186:189], v[130:133]
	v_mfma_f32_16x16x32_bf16 v[126:129], v[174:177], v[186:189], v[126:129]
	v_mfma_f32_16x16x32_bf16 v[114:117], v[166:169], v[194:197], v[114:117]
	v_mfma_f32_16x16x32_bf16 v[102:105], v[174:177], v[194:197], v[102:105]
	v_mfma_f32_16x16x32_bf16 v[92:95], v[166:169], v[202:205], v[92:95]
	v_mfma_f32_16x16x32_bf16 v[80:83], v[174:177], v[202:205], v[80:83]
	v_mfma_f32_16x16x32_bf16 v[76:79], v[166:169], v[210:213], v[76:79]
	v_mfma_f32_16x16x32_bf16 v[64:67], v[174:177], v[210:213], v[64:67]
	v_mfma_f32_16x16x32_bf16 v[130:133], v[170:173], v[190:193], v[130:133]
	v_mfma_f32_16x16x32_bf16 v[126:129], v[178:181], v[190:193], v[126:129]
	v_mfma_f32_16x16x32_bf16 v[114:117], v[170:173], v[198:201], v[114:117]
	v_mfma_f32_16x16x32_bf16 v[102:105], v[178:181], v[198:201], v[102:105]
	v_mfma_f32_16x16x32_bf16 v[92:95], v[170:173], v[206:209], v[92:95]
	v_mfma_f32_16x16x32_bf16 v[80:83], v[178:181], v[206:209], v[80:83]
	v_mfma_f32_16x16x32_bf16 v[76:79], v[170:173], v[214:217], v[76:79]
	v_mfma_f32_16x16x32_bf16 v[64:67], v[178:181], v[214:217], v[64:67]
	s_setprio 0
	s_barrier
	s_add_i32 s78, s78, s62
	v_lshl_add_u64 v[160:161], s[58:59], 0, v[96:97]
	s_mov_b32 m0, s78
	ds_read_b128 v[186:189], v165 offset:16384
	ds_read_b128 v[190:193], v165 offset:17408
	ds_read_b128 v[194:197], v165 offset:18432
	ds_read_b128 v[198:201], v165 offset:19456
	ds_read_b128 v[202:205], v165 offset:20480
	ds_read_b128 v[206:209], v165 offset:21504
	ds_read_b128 v[210:213], v165 offset:22528
	ds_read_b128 v[214:217], v165 offset:23552
	global_load_lds_dwordx4 v[160:161], off
	s_add_i32 m0, s78, 0x2000
	s_add_u32 s78, s58, 0x80000
	v_lshl_add_u64 v[218:219], s[58:59], 0, v[98:99]
	s_addc_u32 s79, s59, 0
	s_add_i32 s80, s80, s62
	global_load_lds_dwordx4 v[218:219], off
	v_lshl_add_u64 v[220:221], s[78:79], 0, v[96:97]
	s_mov_b32 m0, s80
	v_lshl_add_u64 v[222:223], s[60:61], 0, v[134:135]
	global_load_lds_dwordx4 v[220:221], off
	v_lshl_add_u64 v[220:221], s[78:79], 0, v[98:99]
	s_add_i32 m0, s80, 0x2000
	s_nop 0
	global_load_lds_dwordx4 v[220:221], off
	v_lshl_add_u64 v[220:221], s[60:61], 0, v[136:137]
	s_mov_b32 m0, s63
	s_nop 0
	global_load_lds_dwordx4 v[220:221], off
	s_mov_b32 m0, s64
	s_nop 0
	global_load_lds_dwordx4 v[222:223], off
	s_waitcnt vmcnt(8)
	s_waitcnt lgkmcnt(0)
	s_barrier
; #define PG8_STAGE(bufoff, gbase, voff) do { _Pragma("unroll") for (int _i = 0; _i < 2; ++_i) \
;         __builtin_amdgcn_global_load_lds((const unsigned*)((const char*)(gbase) + (voff)[_i]), (PG8_LAS unsigned*)(lds + (bufoff) + ldsw + _i * 8192), 16, 0, 0); } while (0)
; #define PG8_LDA(dst, b, h) do { _Pragma("unroll") for (int m = 0; m < 4; ++m) _Pragma("unroll") for (int k = 0; k < 2; ++k) dst[m][k] = *(const PG8_LAS bf16x8*)(lds + PG8_SA(b, h) + aoff + m * 2048 + k * 1024); } while (0)
; #define PG8_LDB(dst, b, h) do { _Pragma("unroll") for (int n = 0; n < 2; ++n) _Pragma("unroll") for (int k = 0; k < 2; ++k) dst[n][k] = *(const PG8_LAS bf16x8*)(lds + PG8_SB(b, h) + boff + n * 2048 + k * 1024); } while (0)
; #define PG8_MMA(ai, bj, At, Bt) do { __builtin_amdgcn_s_setprio(1); _Pragma("unroll") for (int m = 0; m < 4; ++m) _Pragma("unroll") for (int n = 0; n < 2; ++n) _Pragma("unroll") for (int k = 0; k < 2; ++k) \
;         acc[ai][bj][m][n] = __builtin_amdgcn_mfma_f32_16x16x32_bf16(Bt[n][k], At[m][k], acc[ai][bj][m][n], 0, 0, 0); __builtin_amdgcn_s_setprio(0); } while (0)
; #define PG8_WAIT_V(n) asm volatile("s_waitcnt vmcnt(" #n ")" ::: "memory")
; #define PG8_WAIT_L(n) asm volatile("s_waitcnt lgkmcnt(" #n ")" ::: "memory")
; #define PG8_BAR __builtin_amdgcn_s_barrier()
; #define PG8_SCHED __builtin_amdgcn_sched_barrier(0)
; template <class Epi, class Sched, bool ALIGN_EPI = false, bool SP2 = false>
; __device__ __forceinline__ void gemm_phase(PG8_LAS unsigned char* lds, const Gemm g, const Sched& S, const Epi& E, const int tid) {
;     ...
;             PG8_WAIT_V(8); PG8_WAIT_L(0); PG8_BAR; PG8_MMA(1, 0, At, B0); PG8_MMA(1, 1, At, B1); PG8_BAR; PG8_SCHED;
;             PG8_LDB(B0, 1, 0); PG8_LDB(B1, 1, 1); PG8_SCHED; PG8_LDA(At, 1, 0); PG8_STAGE(PG8_SA(0, 1), a2 + hstep, voffA);
;             PG8_WAIT_V(8); PG8_WAIT_L(0); PG8_BAR; PG8_MMA(0, 0, At, B0); PG8_MMA(0, 1, At, B1); PG8_BAR; PG8_SCHED;
	s_setprio 1
	v_mfma_f32_16x16x32_bf16 v[56:59], v[144:147], v[186:189], v[56:59]
	v_mfma_f32_16x16x32_bf16 v[52:55], v[152:155], v[186:189], v[52:55]
	v_mfma_f32_16x16x32_bf16 v[40:43], v[144:147], v[194:197], v[40:43]
	v_mfma_f32_16x16x32_bf16 v[36:39], v[152:155], v[194:197], v[36:39]
	v_mfma_f32_16x16x32_bf16 v[24:27], v[144:147], v[202:205], v[24:27]
	v_mfma_f32_16x16x32_bf16 v[20:23], v[152:155], v[202:205], v[20:23]
	v_mfma_f32_16x16x32_bf16 v[8:11], v[144:147], v[210:213], v[8:11]
	v_mfma_f32_16x16x32_bf16 v[4:7], v[152:155], v[210:213], v[4:7]
	v_mfma_f32_16x16x32_bf16 v[56:59], v[148:151], v[190:193], v[56:59]
	v_mfma_f32_16x16x32_bf16 v[52:55], v[156:159], v[190:193], v[52:55]
	v_mfma_f32_16x16x32_bf16 v[40:43], v[148:151], v[198:201], v[40:43]
	v_mfma_f32_16x16x32_bf16 v[36:39], v[156:159], v[198:201], v[36:39]
	v_mfma_f32_16x16x32_bf16 v[24:27], v[148:151], v[206:209], v[24:27]
	v_mfma_f32_16x16x32_bf16 v[20:23], v[156:159], v[206:209], v[20:23]
	v_mfma_f32_16x16x32_bf16 v[8:11], v[148:151], v[214:217], v[8:11]
	v_mfma_f32_16x16x32_bf16 v[4:7], v[156:159], v[214:217], v[4:7]
	v_mfma_f32_16x16x32_bf16 v[60:63], v[166:169], v[186:189], v[60:63]
	v_mfma_f32_16x16x32_bf16 v[48:51], v[174:177], v[186:189], v[48:51]
	v_mfma_f32_16x16x32_bf16 v[44:47], v[166:169], v[194:197], v[44:47]
	v_mfma_f32_16x16x32_bf16 v[32:35], v[174:177], v[194:197], v[32:35]
	v_mfma_f32_16x16x32_bf16 v[28:31], v[166:169], v[202:205], v[28:31]
	v_mfma_f32_16x16x32_bf16 v[16:19], v[174:177], v[202:205], v[16:19]
	v_mfma_f32_16x16x32_bf16 v[12:15], v[166:169], v[210:213], v[12:15]
	v_mfma_f32_16x16x32_bf16 v[0:3], v[174:177], v[210:213], v[0:3]
	v_mfma_f32_16x16x32_bf16 v[60:63], v[170:173], v[190:193], v[60:63]
	v_mfma_f32_16x16x32_bf16 v[48:51], v[178:181], v[190:193], v[48:51]
	v_mfma_f32_16x16x32_bf16 v[44:47], v[170:173], v[198:201], v[44:47]
	v_mfma_f32_16x16x32_bf16 v[32:35], v[178:181], v[198:201], v[32:35]
	v_mfma_f32_16x16x32_bf16 v[28:31], v[170:173], v[206:209], v[28:31]
	v_mfma_f32_16x16x32_bf16 v[16:19], v[178:181], v[206:209], v[16:19]
	v_mfma_f32_16x16x32_bf16 v[12:15], v[170:173], v[214:217], v[12:15]
	v_mfma_f32_16x16x32_bf16 v[0:3], v[178:181], v[214:217], v[0:3]
	s_setprio 0
	s_barrier
	s_add_i32 s78, 0, 0x18000
	s_add_i32 s79, 0, 0x1c000
	v_add_u32_e32 v156, s78, v163
	v_add_u32_e32 v162, s79, v163
	ds_read_b128 v[144:147], v156
	ds_read_b128 v[148:151], v156 offset:1024
	ds_read_b128 v[152:155], v156 offset:2048
	ds_read_b128 v[156:159], v156 offset:3072
	ds_read_b128 v[166:169], v162
	ds_read_b128 v[170:173], v162 offset:1024
	ds_read_b128 v[174:177], v162 offset:2048
	ds_read_b128 v[178:181], v162 offset:3072
	s_add_u32 s60, s60, 0x80000
	s_addc_u32 s61, s61, 0
	s_mov_b32 m0, s65
	v_lshl_add_u64 v[224:225], s[60:61], 0, v[136:137]
	ds_read_b128 v[186:189], v165 offset:32768
	ds_read_b128 v[190:193], v165 offset:33792
	ds_read_b128 v[194:197], v165 offset:34816
	ds_read_b128 v[198:201], v165 offset:35840
	ds_read_b128 v[202:205], v165 offset:36864
	ds_read_b128 v[206:209], v165 offset:37888
	ds_read_b128 v[210:213], v165 offset:38912
	ds_read_b128 v[214:217], v165 offset:39936
	global_load_lds_dwordx4 v[224:225], off
	v_lshl_add_u64 v[224:225], s[60:61], 0, v[134:135]
	s_mov_b32 m0, s66
	s_nop 0
	global_load_lds_dwordx4 v[224:225], off
	s_waitcnt vmcnt(8)
	s_waitcnt lgkmcnt(0)
	s_barrier
	s_setprio 1
	v_mfma_f32_16x16x32_bf16 v[122:125], v[144:147], v[186:189], v[122:125]
	v_mfma_f32_16x16x32_bf16 v[118:121], v[152:155], v[186:189], v[118:121]
	v_mfma_f32_16x16x32_bf16 v[110:113], v[144:147], v[194:197], v[110:113]
	v_mfma_f32_16x16x32_bf16 v[106:109], v[152:155], v[194:197], v[106:109]
	v_mfma_f32_16x16x32_bf16 v[88:91], v[144:147], v[202:205], v[88:91]
	v_mfma_f32_16x16x32_bf16 v[84:87], v[152:155], v[202:205], v[84:87]
	v_mfma_f32_16x16x32_bf16 v[72:75], v[144:147], v[210:213], v[72:75]
	v_mfma_f32_16x16x32_bf16 v[68:71], v[152:155], v[210:213], v[68:71]
	v_mfma_f32_16x16x32_bf16 v[122:125], v[148:151], v[190:193], v[122:125]
	v_mfma_f32_16x16x32_bf16 v[118:121], v[156:159], v[190:193], v[118:121]
	v_mfma_f32_16x16x32_bf16 v[110:113], v[148:151], v[198:201], v[110:113]
	v_mfma_f32_16x16x32_bf16 v[106:109], v[156:159], v[198:201], v[106:109]
	v_mfma_f32_16x16x32_bf16 v[88:91], v[148:151], v[206:209], v[88:91]
	v_mfma_f32_16x16x32_bf16 v[84:87], v[156:159], v[206:209], v[84:87]
	v_mfma_f32_16x16x32_bf16 v[72:75], v[148:151], v[214:217], v[72:75]
	v_mfma_f32_16x16x32_bf16 v[68:71], v[156:159], v[214:217], v[68:71]
	v_mfma_f32_16x16x32_bf16 v[130:133], v[166:169], v[186:189], v[130:133]
	v_mfma_f32_16x16x32_bf16 v[126:129], v[174:177], v[186:189], v[126:129]
	v_mfma_f32_16x16x32_bf16 v[114:117], v[166:169], v[194:197], v[114:117]
	v_mfma_f32_16x16x32_bf16 v[102:105], v[174:177], v[194:197], v[102:105]
	v_mfma_f32_16x16x32_bf16 v[92:95], v[166:169], v[202:205], v[92:95]
	v_mfma_f32_16x16x32_bf16 v[80:83], v[174:177], v[202:205], v[80:83]
	v_mfma_f32_16x16x32_bf16 v[76:79], v[166:169], v[210:213], v[76:79]
	v_mfma_f32_16x16x32_bf16 v[64:67], v[174:177], v[210:213], v[64:67]
	v_mfma_f32_16x16x32_bf16 v[130:133], v[170:173], v[190:193], v[130:133]
	v_mfma_f32_16x16x32_bf16 v[126:129], v[178:181], v[190:193], v[126:129]
	v_mfma_f32_16x16x32_bf16 v[114:117], v[170:173], v[198:201], v[114:117]
	v_mfma_f32_16x16x32_bf16 v[102:105], v[178:181], v[198:201], v[102:105]
	v_mfma_f32_16x16x32_bf16 v[92:95], v[170:173], v[206:209], v[92:95]
	v_mfma_f32_16x16x32_bf16 v[80:83], v[178:181], v[206:209], v[80:83]
	v_mfma_f32_16x16x32_bf16 v[76:79], v[170:173], v[214:217], v[76:79]
	v_mfma_f32_16x16x32_bf16 v[64:67], v[178:181], v[214:217], v[64:67]
	s_setprio 0
	s_barrier
; #define PG8_STAGE(bufoff, gbase, voff) do { _Pragma("unroll") for (int _i = 0; _i < 2; ++_i) \
;         __builtin_amdgcn_global_load_lds((const unsigned*)((const char*)(gbase) + (voff)[_i]), (PG8_LAS unsigned*)(lds + (bufoff) + ldsw + _i * 8192), 16, 0, 0); } while (0)
; #define PG8_LDA(dst, b, h) do { _Pragma("unroll") for (int m = 0; m < 4; ++m) _Pragma("unroll") for (int k = 0; k < 2; ++k) dst[m][k] = *(const PG8_LAS bf16x8*)(lds + PG8_SA(b, h) + aoff + m * 2048 + k * 1024); } while (0)
; #define PG8_MMA(ai, bj, At, Bt) do { __builtin_amdgcn_s_setprio(1); _Pragma("unroll") for (int m = 0; m < 4; ++m) _Pragma("unroll") for (int n = 0; n < 2; ++n) _Pragma("unroll") for (int k = 0; k < 2; ++k) \
;         acc[ai][bj][m][n] = __builtin_amdgcn_mfma_f32_16x16x32_bf16(Bt[n][k], At[m][k], acc[ai][bj][m][n], 0, 0, 0); __builtin_amdgcn_s_setprio(0); } while (0)
; #define PG8_WAIT_V(n) asm volatile("s_waitcnt vmcnt(" #n ")" ::: "memory")
; #define PG8_WAIT_L(n) asm volatile("s_waitcnt lgkmcnt(" #n ")" ::: "memory")
; #define PG8_BAR __builtin_amdgcn_s_barrier()
; #define PG8_SCHED __builtin_amdgcn_sched_barrier(0)
; template <class Epi, class Sched, bool ALIGN_EPI = false, bool SP2 = false>
; __device__ __forceinline__ void gemm_phase(PG8_LAS unsigned char* lds, const Gemm g, const Sched& S, const Epi& E, const int tid) {
;     ...
;             PG8_LDA(At, 1, 1); PG8_STAGE(PG8_SB(1, 0), b3, voffB); PG8_STAGE(PG8_SB(1, 1), b3 + hstep, voffB); PG8_STAGE(PG8_SA(1, 0), a3, voffA);
;             PG8_WAIT_V(8); PG8_WAIT_L(0); PG8_BAR; PG8_MMA(1, 0, At, B0); PG8_MMA(1, 1, At, B1); PG8_BAR; PG8_SCHED;
	s_add_i32 s60, s78, s62
	v_lshl_add_u64 v[160:161], v[160:161], 0, s[28:29]
	s_mov_b32 m0, s60
	ds_read_b128 v[186:189], v165 offset:49152
	ds_read_b128 v[190:193], v165 offset:50176
	ds_read_b128 v[194:197], v165 offset:51200
	ds_read_b128 v[198:201], v165 offset:52224
	ds_read_b128 v[202:205], v165 offset:53248
	ds_read_b128 v[206:209], v165 offset:54272
	ds_read_b128 v[210:213], v165 offset:55296
	ds_read_b128 v[214:217], v165 offset:56320
	global_load_lds_dwordx4 v[160:161], off
	s_add_i32 m0, s60, 0x2000
	s_add_u32 s58, s58, 0x80080
	v_lshl_add_u64 v[160:161], v[218:219], 0, s[28:29]
	s_addc_u32 s59, s59, 0
	s_add_i32 s60, s79, s62
	global_load_lds_dwordx4 v[160:161], off
	v_lshl_add_u64 v[160:161], s[58:59], 0, v[96:97]
	s_mov_b32 m0, s60
	s_nop 0
	global_load_lds_dwordx4 v[160:161], off
	v_lshl_add_u64 v[160:161], s[58:59], 0, v[98:99]
	s_add_i32 m0, s60, 0x2000
	s_nop 0
	global_load_lds_dwordx4 v[160:161], off
	v_lshl_add_u64 v[160:161], v[220:221], 0, s[28:29]
	s_mov_b32 m0, s67
	s_nop 0
	global_load_lds_dwordx4 v[160:161], off
	v_lshl_add_u64 v[160:161], v[222:223], 0, s[28:29]
	s_mov_b32 m0, s68
	s_nop 0
	global_load_lds_dwordx4 v[160:161], off
	s_waitcnt vmcnt(8)
	s_waitcnt lgkmcnt(0)
	s_barrier
	s_setprio 1
	v_mfma_f32_16x16x32_bf16 v[56:59], v[144:147], v[186:189], v[56:59]
	v_mfma_f32_16x16x32_bf16 v[52:55], v[152:155], v[186:189], v[52:55]
	v_mfma_f32_16x16x32_bf16 v[40:43], v[144:147], v[194:197], v[40:43]
	v_mfma_f32_16x16x32_bf16 v[36:39], v[152:155], v[194:197], v[36:39]
	v_mfma_f32_16x16x32_bf16 v[24:27], v[144:147], v[202:205], v[24:27]
	v_mfma_f32_16x16x32_bf16 v[20:23], v[152:155], v[202:205], v[20:23]
	v_mfma_f32_16x16x32_bf16 v[8:11], v[144:147], v[210:213], v[8:11]
	v_mfma_f32_16x16x32_bf16 v[4:7], v[152:155], v[210:213], v[4:7]
	v_mfma_f32_16x16x32_bf16 v[56:59], v[148:151], v[190:193], v[56:59]
	v_mfma_f32_16x16x32_bf16 v[52:55], v[156:159], v[190:193], v[52:55]
	v_mfma_f32_16x16x32_bf16 v[40:43], v[148:151], v[198:201], v[40:43]
	v_mfma_f32_16x16x32_bf16 v[36:39], v[156:159], v[198:201], v[36:39]
	v_mfma_f32_16x16x32_bf16 v[24:27], v[148:151], v[206:209], v[24:27]
	v_mfma_f32_16x16x32_bf16 v[20:23], v[156:159], v[206:209], v[20:23]
	v_mfma_f32_16x16x32_bf16 v[8:11], v[148:151], v[214:217], v[8:11]
	v_mfma_f32_16x16x32_bf16 v[4:7], v[156:159], v[214:217], v[4:7]
	v_mfma_f32_16x16x32_bf16 v[60:63], v[166:169], v[186:189], v[60:63]
	v_mfma_f32_16x16x32_bf16 v[48:51], v[174:177], v[186:189], v[48:51]
	v_mfma_f32_16x16x32_bf16 v[44:47], v[166:169], v[194:197], v[44:47]
	v_mfma_f32_16x16x32_bf16 v[32:35], v[174:177], v[194:197], v[32:35]
	v_mfma_f32_16x16x32_bf16 v[28:31], v[166:169], v[202:205], v[28:31]
	v_mfma_f32_16x16x32_bf16 v[16:19], v[174:177], v[202:205], v[16:19]
	v_mfma_f32_16x16x32_bf16 v[12:15], v[166:169], v[210:213], v[12:15]
	v_mfma_f32_16x16x32_bf16 v[0:3], v[174:177], v[210:213], v[0:3]
	v_mfma_f32_16x16x32_bf16 v[60:63], v[170:173], v[190:193], v[60:63]
	v_mfma_f32_16x16x32_bf16 v[48:51], v[178:181], v[190:193], v[48:51]
	v_mfma_f32_16x16x32_bf16 v[44:47], v[170:173], v[198:201], v[44:47]
	v_mfma_f32_16x16x32_bf16 v[32:35], v[178:181], v[198:201], v[32:35]
	v_mfma_f32_16x16x32_bf16 v[28:31], v[170:173], v[206:209], v[28:31]
	v_mfma_f32_16x16x32_bf16 v[16:19], v[178:181], v[206:209], v[16:19]
	v_mfma_f32_16x16x32_bf16 v[12:15], v[170:173], v[214:217], v[12:15]
	v_mfma_f32_16x16x32_bf16 v[0:3], v[178:181], v[214:217], v[0:3]
	s_setprio 0
	s_barrier
	s_add_i32 s77, s77, 2
	s_add_u32 s75, s75, 0x100
	s_addc_u32 s76, s76, 0
	s_add_u32 s42, s42, 0x100
	s_addc_u32 s43, s43, 0
	s_cmp_gt_u32 s77, 29
	s_cbranch_scc0 .LBB0_488
	s_and_b64 vcc, exec, s[46:47]
	s_cbranch_vccz .LBB0_491
	s_barrier

; #define PG8_STAGE(bufoff, gbase, voff) do { _Pragma("unroll") for (int _i = 0; _i < 2; ++_i) \
;         __builtin_amdgcn_global_load_lds((const unsigned*)((const char*)(gbase) + (voff)[_i]), (PG8_LAS unsigned*)(lds + (bufoff) + ldsw + _i * 8192), 16, 0, 0); } while (0)
; #define PG8_LDA(dst, b, h) do { _Pragma("unroll") for (int m = 0; m < 4; ++m) _Pragma("unroll") for (int k = 0; k < 2; ++k) dst[m][k] = *(const PG8_LAS bf16x8*)(lds + PG8_SA(b, h) + aoff + m * 2048 + k * 1024); } while (0)
; #define PG8_LDB(dst, b, h) do { _Pragma("unroll") for (int n = 0; n < 2; ++n) _Pragma("unroll") for (int k = 0; k < 2; ++k) dst[n][k] = *(const PG8_LAS bf16x8*)(lds + PG8_SB(b, h) + boff + n * 2048 + k * 1024); } while (0)
; #define PG8_MMA(ai, bj, At, Bt) do { __builtin_amdgcn_s_setprio(1); _Pragma("unroll") for (int m = 0; m < 4; ++m) _Pragma("unroll") for (int n = 0; n < 2; ++n) _Pragma("unroll") for (int k = 0; k < 2; ++k) \
;         acc[ai][bj][m][n] = __builtin_amdgcn_mfma_f32_16x16x32_bf16(Bt[n][k], At[m][k], acc[ai][bj][m][n], 0, 0, 0); __builtin_amdgcn_s_setprio(0); } while (0)
; #define PG8_WAIT_V(n) asm volatile("s_waitcnt vmcnt(" #n ")" ::: "memory")
; #define PG8_WAIT_L(n) asm volatile("s_waitcnt lgkmcnt(" #n ")" ::: "memory")
; template <class Epi, class Sched, bool ALIGN_EPI = false, bool SP2 = false>
; __device__ __forceinline__ void gemm_phase(PG8_LAS unsigned char* lds, const Gemm g, const Sched& S, const Epi& E, const int tid) {
;     ...
;             const bool last = (t == nt - 2);
;             const char* a1 = cA + (size_t)(t + 1) * kstep;
;             const char* a2 = last ? nA : cA + (size_t)(t + 2) * kstep; const char* b2 = last ? nB : cB + (size_t)(t + 2) * kstep;
;             const char* a3 = a2 + kstep; const char* b3 = b2 + kstep;
;             if (last && has_next) S.a_ready(nxt);
;             if constexpr (SP2) {
;             PG8_LDB(B0, 0, 0); PG8_LDB(B1, 0, 1); PG8_SCHED; PG8_LDA(At, 0, 0); PG8_STAGE(PG8_SA(1, 1), a1 + hstep, voffA);
;             PG8_WAIT_V(8); PG8_WAIT_L(0); PG8_BAR; PG8_MMA(0, 0, At, B0); PG8_MMA(0, 1, At, B1); PG8_BAR; PG8_SCHED;
;             PG8_LDA(At, 0, 1); PG8_STAGE(PG8_SB(0, 0), b2, voffB); PG8_STAGE(PG8_SB(0, 1), b2 + hstep, voffB); PG8_STAGE(PG8_SA(0, 0), a2, voffA);
;             PG8_WAIT_V(8); PG8_WAIT_L(0); PG8_BAR; PG8_MMA(1, 0, At, B0); PG8_MMA(1, 1, At, B1); PG8_BAR; PG8_SCHED;
.LBB0_1199:
	s_add_u32 s56, s54, 0xfff80080
	s_addc_u32 s57, s55, -1
	s_add_i32 s77, 0, 0x10000
	s_cmp_eq_u32 s76, 28
	s_cselect_b32 s59, s49, s57
	s_cselect_b32 s58, s71, s56
	s_cselect_b32 s57, s47, s75
	s_cselect_b32 s56, s72, s73
	s_add_i32 s80, 0, 0x14000
	v_add_u32_e32 v146, s77, v233
	v_add_u32_e32 v162, s80, v233
	ds_read_b128 v[126:129], v146
	ds_read_b128 v[130:133], v146 offset:1024
	ds_read_b128 v[142:145], v146 offset:2048
	ds_read_b128 v[146:149], v146 offset:3072
	ds_read_b128 v[150:153], v162
	ds_read_b128 v[154:157], v162 offset:1024
	ds_read_b128 v[158:161], v162 offset:2048
	ds_read_b128 v[162:165], v162 offset:3072
	v_lshl_add_u64 v[210:211], s[54:55], 0, v[192:193]
	s_add_i32 m0, s62, 0xc000
	ds_read_b128 v[166:169], v236
	ds_read_b128 v[170:173], v236 offset:1024
	ds_read_b128 v[174:177], v236 offset:2048
	ds_read_b128 v[178:181], v236 offset:3072
	ds_read_b128 v[194:197], v236 offset:4096
	ds_read_b128 v[198:201], v236 offset:5120
	ds_read_b128 v[202:205], v236 offset:6144
	ds_read_b128 v[206:209], v236 offset:7168
	global_load_lds_dwordx4 v[210:211], off
	v_lshl_add_u64 v[210:211], s[54:55], 0, v[190:191]
	s_add_i32 m0, s62, 0xe000
	s_nop 0
	global_load_lds_dwordx4 v[210:211], off
	s_waitcnt vmcnt(8)
	s_waitcnt lgkmcnt(0)
	s_barrier
	s_setprio 1
	v_mfma_f32_16x16x32_bf16 v[138:141], v[126:129], v[166:169], v[138:141]
	v_mfma_f32_16x16x32_bf16 v[134:137], v[142:145], v[166:169], v[134:137]
	v_mfma_f32_16x16x32_bf16 v[114:117], v[126:129], v[174:177], v[114:117]
	v_mfma_f32_16x16x32_bf16 v[110:113], v[142:145], v[174:177], v[110:113]
	v_mfma_f32_16x16x32_bf16 v[92:95], v[126:129], v[194:197], v[92:95]
	v_mfma_f32_16x16x32_bf16 v[88:91], v[142:145], v[194:197], v[88:91]
	v_mfma_f32_16x16x32_bf16 v[76:79], v[126:129], v[202:205], v[76:79]
	v_mfma_f32_16x16x32_bf16 v[72:75], v[142:145], v[202:205], v[72:75]
	v_mfma_f32_16x16x32_bf16 v[138:141], v[130:133], v[170:173], v[138:141]
	v_mfma_f32_16x16x32_bf16 v[134:137], v[146:149], v[170:173], v[134:137]
	v_mfma_f32_16x16x32_bf16 v[114:117], v[130:133], v[178:181], v[114:117]
	v_mfma_f32_16x16x32_bf16 v[110:113], v[146:149], v[178:181], v[110:113]
	v_mfma_f32_16x16x32_bf16 v[92:95], v[130:133], v[198:201], v[92:95]
	v_mfma_f32_16x16x32_bf16 v[88:91], v[146:149], v[198:201], v[88:91]
	v_mfma_f32_16x16x32_bf16 v[76:79], v[130:133], v[206:209], v[76:79]
	v_mfma_f32_16x16x32_bf16 v[72:75], v[146:149], v[206:209], v[72:75]
	v_mfma_f32_16x16x32_bf16 v[122:125], v[150:153], v[166:169], v[122:125]
	v_mfma_f32_16x16x32_bf16 v[118:121], v[158:161], v[166:169], v[118:121]
	v_mfma_f32_16x16x32_bf16 v[106:109], v[150:153], v[174:177], v[106:109]
	v_mfma_f32_16x16x32_bf16 v[102:105], v[158:161], v[174:177], v[102:105]
	v_mfma_f32_16x16x32_bf16 v[84:87], v[150:153], v[194:197], v[84:87]
	v_mfma_f32_16x16x32_bf16 v[80:83], v[158:161], v[194:197], v[80:83]
	v_mfma_f32_16x16x32_bf16 v[68:71], v[150:153], v[202:205], v[68:71]
	v_mfma_f32_16x16x32_bf16 v[64:67], v[158:161], v[202:205], v[64:67]
	v_mfma_f32_16x16x32_bf16 v[122:125], v[154:157], v[170:173], v[122:125]
	v_mfma_f32_16x16x32_bf16 v[118:121], v[162:165], v[170:173], v[118:121]
	v_mfma_f32_16x16x32_bf16 v[106:109], v[154:157], v[178:181], v[106:109]
	v_mfma_f32_16x16x32_bf16 v[102:105], v[162:165], v[178:181], v[102:105]
	v_mfma_f32_16x16x32_bf16 v[84:87], v[154:157], v[198:201], v[84:87]
	v_mfma_f32_16x16x32_bf16 v[80:83], v[162:165], v[198:201], v[80:83]
	v_mfma_f32_16x16x32_bf16 v[68:71], v[154:157], v[206:209], v[68:71]
	v_mfma_f32_16x16x32_bf16 v[64:67], v[162:165], v[206:209], v[64:67]
	s_setprio 0
	s_barrier
	s_add_i32 s77, s77, s61
	v_lshl_add_u64 v[210:211], s[56:57], 0, v[96:97]
	s_mov_b32 m0, s77
	ds_read_b128 v[166:169], v236 offset:16384
	ds_read_b128 v[170:173], v236 offset:17408
	ds_read_b128 v[174:177], v236 offset:18432
	ds_read_b128 v[178:181], v236 offset:19456
	ds_read_b128 v[194:197], v236 offset:20480
	ds_read_b128 v[198:201], v236 offset:21504
	ds_read_b128 v[202:205], v236 offset:22528
	ds_read_b128 v[206:209], v236 offset:23552
	global_load_lds_dwordx4 v[210:211], off
	s_add_i32 m0, s77, 0x2000
	s_add_u32 s78, s56, 0x80000
	v_lshl_add_u64 v[212:213], s[56:57], 0, v[98:99]
	s_addc_u32 s79, s57, 0
	s_add_i32 s77, s80, s61
	global_load_lds_dwordx4 v[212:213], off
	v_lshl_add_u64 v[214:215], s[78:79], 0, v[96:97]
	s_mov_b32 m0, s77
	v_lshl_add_u64 v[216:217], s[58:59], 0, v[186:187]
	global_load_lds_dwordx4 v[214:215], off
	v_lshl_add_u64 v[214:215], s[78:79], 0, v[98:99]
	s_add_i32 m0, s77, 0x2000
	s_nop 0
	global_load_lds_dwordx4 v[214:215], off
	v_lshl_add_u64 v[214:215], s[58:59], 0, v[188:189]
	s_mov_b32 m0, s62
	s_nop 0
	global_load_lds_dwordx4 v[214:215], off
	s_mov_b32 m0, s63
	s_nop 0
	global_load_lds_dwordx4 v[216:217], off
	s_waitcnt vmcnt(8)
	s_waitcnt lgkmcnt(0)
	s_barrier
; #define PG8_STAGE(bufoff, gbase, voff) do { _Pragma("unroll") for (int _i = 0; _i < 2; ++_i) \
;         __builtin_amdgcn_global_load_lds((const unsigned*)((const char*)(gbase) + (voff)[_i]), (PG8_LAS unsigned*)(lds + (bufoff) + ldsw + _i * 8192), 16, 0, 0); } while (0)
; #define PG8_LDA(dst, b, h) do { _Pragma("unroll") for (int m = 0; m < 4; ++m) _Pragma("unroll") for (int k = 0; k < 2; ++k) dst[m][k] = *(const PG8_LAS bf16x8*)(lds + PG8_SA(b, h) + aoff + m * 2048 + k * 1024); } while (0)
; #define PG8_LDB(dst, b, h) do { _Pragma("unroll") for (int n = 0; n < 2; ++n) _Pragma("unroll") for (int k = 0; k < 2; ++k) dst[n][k] = *(const PG8_LAS bf16x8*)(lds + PG8_SB(b, h) + boff + n * 2048 + k * 1024); } while (0)
; #define PG8_MMA(ai, bj, At, Bt) do { __builtin_amdgcn_s_setprio(1); _Pragma("unroll") for (int m = 0; m < 4; ++m) _Pragma("unroll") for (int n = 0; n < 2; ++n) _Pragma("unroll") for (int k = 0; k < 2; ++k) \
;         acc[ai][bj][m][n] = __builtin_amdgcn_mfma_f32_16x16x32_bf16(Bt[n][k], At[m][k], acc[ai][bj][m][n], 0, 0, 0); __builtin_amdgcn_s_setprio(0); } while (0)
; #define PG8_WAIT_V(n) asm volatile("s_waitcnt vmcnt(" #n ")" ::: "memory")
; #define PG8_WAIT_L(n) asm volatile("s_waitcnt lgkmcnt(" #n ")" ::: "memory")
; #define PG8_BAR __builtin_amdgcn_s_barrier()
; #define PG8_SCHED __builtin_amdgcn_sched_barrier(0)
; template <class Epi, class Sched, bool ALIGN_EPI = false, bool SP2 = false>
; __device__ __forceinline__ void gemm_phase(PG8_LAS unsigned char* lds, const Gemm g, const Sched& S, const Epi& E, const int tid) {
;     ...
;             PG8_WAIT_V(8); PG8_WAIT_L(0); PG8_BAR; PG8_MMA(0, 0, At, B0); PG8_MMA(0, 1, At, B1); PG8_BAR; PG8_SCHED;
;             PG8_LDA(At, 0, 1); PG8_STAGE(PG8_SB(0, 0), b2, voffB); PG8_STAGE(PG8_SB(0, 1), b2 + hstep, voffB); PG8_STAGE(PG8_SA(0, 0), a2, voffA);
;             PG8_WAIT_V(8); PG8_WAIT_L(0); PG8_BAR; PG8_MMA(1, 0, At, B0); PG8_MMA(1, 1, At, B1); PG8_BAR; PG8_SCHED;
;             PG8_LDB(B0, 1, 0); PG8_LDB(B1, 1, 1); PG8_SCHED; PG8_LDA(At, 1, 0); PG8_STAGE(PG8_SA(0, 1), a2 + hstep, voffA);
;             PG8_WAIT_V(8); PG8_WAIT_L(0); PG8_BAR; PG8_MMA(0, 0, At, B0); PG8_MMA(0, 1, At, B1); PG8_BAR; PG8_SCHED;
	s_setprio 1
	v_mfma_f32_16x16x32_bf16 v[60:63], v[126:129], v[166:169], v[60:63]
	v_mfma_f32_16x16x32_bf16 v[56:59], v[142:145], v[166:169], v[56:59]
	v_mfma_f32_16x16x32_bf16 v[44:47], v[126:129], v[174:177], v[44:47]
	v_mfma_f32_16x16x32_bf16 v[40:43], v[142:145], v[174:177], v[40:43]
	v_mfma_f32_16x16x32_bf16 v[28:31], v[126:129], v[194:197], v[28:31]
	v_mfma_f32_16x16x32_bf16 v[24:27], v[142:145], v[194:197], v[24:27]
	v_mfma_f32_16x16x32_bf16 v[12:15], v[126:129], v[202:205], v[12:15]
	v_mfma_f32_16x16x32_bf16 v[8:11], v[142:145], v[202:205], v[8:11]
	v_mfma_f32_16x16x32_bf16 v[60:63], v[130:133], v[170:173], v[60:63]
	v_mfma_f32_16x16x32_bf16 v[56:59], v[146:149], v[170:173], v[56:59]
	v_mfma_f32_16x16x32_bf16 v[44:47], v[130:133], v[178:181], v[44:47]
	v_mfma_f32_16x16x32_bf16 v[40:43], v[146:149], v[178:181], v[40:43]
	v_mfma_f32_16x16x32_bf16 v[28:31], v[130:133], v[198:201], v[28:31]
	v_mfma_f32_16x16x32_bf16 v[24:27], v[146:149], v[198:201], v[24:27]
	v_mfma_f32_16x16x32_bf16 v[12:15], v[130:133], v[206:209], v[12:15]
	v_mfma_f32_16x16x32_bf16 v[8:11], v[146:149], v[206:209], v[8:11]
	v_mfma_f32_16x16x32_bf16 v[52:55], v[150:153], v[166:169], v[52:55]
	v_mfma_f32_16x16x32_bf16 v[48:51], v[158:161], v[166:169], v[48:51]
	v_mfma_f32_16x16x32_bf16 v[36:39], v[150:153], v[174:177], v[36:39]
	v_mfma_f32_16x16x32_bf16 v[32:35], v[158:161], v[174:177], v[32:35]
	v_mfma_f32_16x16x32_bf16 v[20:23], v[150:153], v[194:197], v[20:23]
	v_mfma_f32_16x16x32_bf16 v[16:19], v[158:161], v[194:197], v[16:19]
	v_mfma_f32_16x16x32_bf16 v[4:7], v[150:153], v[202:205], v[4:7]
	v_mfma_f32_16x16x32_bf16 v[0:3], v[158:161], v[202:205], v[0:3]
	v_mfma_f32_16x16x32_bf16 v[52:55], v[154:157], v[170:173], v[52:55]
	v_mfma_f32_16x16x32_bf16 v[48:51], v[162:165], v[170:173], v[48:51]
	v_mfma_f32_16x16x32_bf16 v[36:39], v[154:157], v[178:181], v[36:39]
	v_mfma_f32_16x16x32_bf16 v[32:35], v[162:165], v[178:181], v[32:35]
	v_mfma_f32_16x16x32_bf16 v[20:23], v[154:157], v[198:201], v[20:23]
	v_mfma_f32_16x16x32_bf16 v[16:19], v[162:165], v[198:201], v[16:19]
	v_mfma_f32_16x16x32_bf16 v[4:7], v[154:157], v[206:209], v[4:7]
	v_mfma_f32_16x16x32_bf16 v[0:3], v[162:165], v[206:209], v[0:3]
	s_setprio 0
	s_barrier
	s_add_i32 s77, 0, 0x18000
	s_add_i32 s78, 0, 0x1c000
	v_add_u32_e32 v146, s77, v233
	v_add_u32_e32 v162, s78, v233
	ds_read_b128 v[126:129], v146
	ds_read_b128 v[130:133], v146 offset:1024
	ds_read_b128 v[142:145], v146 offset:2048
	ds_read_b128 v[146:149], v146 offset:3072
	ds_read_b128 v[150:153], v162
	ds_read_b128 v[154:157], v162 offset:1024
	ds_read_b128 v[158:161], v162 offset:2048
	ds_read_b128 v[162:165], v162 offset:3072
	s_add_u32 s58, s58, 0x80000
	s_addc_u32 s59, s59, 0
	s_mov_b32 m0, s64
	v_lshl_add_u64 v[218:219], s[58:59], 0, v[188:189]
	ds_read_b128 v[166:169], v236 offset:32768
	ds_read_b128 v[170:173], v236 offset:33792
	ds_read_b128 v[174:177], v236 offset:34816
	ds_read_b128 v[178:181], v236 offset:35840
	ds_read_b128 v[194:197], v236 offset:36864
	ds_read_b128 v[198:201], v236 offset:37888
	ds_read_b128 v[202:205], v236 offset:38912
	ds_read_b128 v[206:209], v236 offset:39936
	global_load_lds_dwordx4 v[218:219], off
	v_lshl_add_u64 v[218:219], s[58:59], 0, v[186:187]
	s_mov_b32 m0, s65
	s_nop 0
	global_load_lds_dwordx4 v[218:219], off
	s_waitcnt vmcnt(8)
	s_waitcnt lgkmcnt(0)
	s_barrier
	s_setprio 1
	v_mfma_f32_16x16x32_bf16 v[138:141], v[126:129], v[166:169], v[138:141]
	v_mfma_f32_16x16x32_bf16 v[134:137], v[142:145], v[166:169], v[134:137]
	v_mfma_f32_16x16x32_bf16 v[114:117], v[126:129], v[174:177], v[114:117]
	v_mfma_f32_16x16x32_bf16 v[110:113], v[142:145], v[174:177], v[110:113]
	v_mfma_f32_16x16x32_bf16 v[92:95], v[126:129], v[194:197], v[92:95]
	v_mfma_f32_16x16x32_bf16 v[88:91], v[142:145], v[194:197], v[88:91]
	v_mfma_f32_16x16x32_bf16 v[76:79], v[126:129], v[202:205], v[76:79]
	v_mfma_f32_16x16x32_bf16 v[72:75], v[142:145], v[202:205], v[72:75]
	v_mfma_f32_16x16x32_bf16 v[138:141], v[130:133], v[170:173], v[138:141]
	v_mfma_f32_16x16x32_bf16 v[134:137], v[146:149], v[170:173], v[134:137]
	v_mfma_f32_16x16x32_bf16 v[114:117], v[130:133], v[178:181], v[114:117]
	v_mfma_f32_16x16x32_bf16 v[110:113], v[146:149], v[178:181], v[110:113]
	v_mfma_f32_16x16x32_bf16 v[92:95], v[130:133], v[198:201], v[92:95]
	v_mfma_f32_16x16x32_bf16 v[88:91], v[146:149], v[198:201], v[88:91]
	v_mfma_f32_16x16x32_bf16 v[76:79], v[130:133], v[206:209], v[76:79]
	v_mfma_f32_16x16x32_bf16 v[72:75], v[146:149], v[206:209], v[72:75]
	v_mfma_f32_16x16x32_bf16 v[122:125], v[150:153], v[166:169], v[122:125]
	v_mfma_f32_16x16x32_bf16 v[118:121], v[158:161], v[166:169], v[118:121]
	v_mfma_f32_16x16x32_bf16 v[106:109], v[150:153], v[174:177], v[106:109]
	v_mfma_f32_16x16x32_bf16 v[102:105], v[158:161], v[174:177], v[102:105]
	v_mfma_f32_16x16x32_bf16 v[84:87], v[150:153], v[194:197], v[84:87]
	v_mfma_f32_16x16x32_bf16 v[80:83], v[158:161], v[194:197], v[80:83]
	v_mfma_f32_16x16x32_bf16 v[68:71], v[150:153], v[202:205], v[68:71]
	v_mfma_f32_16x16x32_bf16 v[64:67], v[158:161], v[202:205], v[64:67]
	v_mfma_f32_16x16x32_bf16 v[122:125], v[154:157], v[170:173], v[122:125]
	v_mfma_f32_16x16x32_bf16 v[118:121], v[162:165], v[170:173], v[118:121]
	v_mfma_f32_16x16x32_bf16 v[106:109], v[154:157], v[178:181], v[106:109]
	v_mfma_f32_16x16x32_bf16 v[102:105], v[162:165], v[178:181], v[102:105]
	v_mfma_f32_16x16x32_bf16 v[84:87], v[154:157], v[198:201], v[84:87]
	v_mfma_f32_16x16x32_bf16 v[80:83], v[162:165], v[198:201], v[80:83]
	v_mfma_f32_16x16x32_bf16 v[68:71], v[154:157], v[206:209], v[68:71]
	v_mfma_f32_16x16x32_bf16 v[64:67], v[162:165], v[206:209], v[64:67]
	s_setprio 0
	s_barrier
; #define PG8_GAS __attribute__((address_space(1)))
; #define PG8_STAGE(bufoff, gbase, voff) do { _Pragma("unroll") for (int _i = 0; _i < 2; ++_i) \
;         __builtin_amdgcn_global_load_lds((const unsigned*)((const char*)(gbase) + (voff)[_i]), (PG8_LAS unsigned*)(lds + (bufoff) + ldsw + _i * 8192), 16, 0, 0); } while (0)
; #define PG8_LDA(dst, b, h) do { _Pragma("unroll") for (int m = 0; m < 4; ++m) _Pragma("unroll") for (int k = 0; k < 2; ++k) dst[m][k] = *(const PG8_LAS bf16x8*)(lds + PG8_SA(b, h) + aoff + m * 2048 + k * 1024); } while (0)
; #define PG8_MMA(ai, bj, At, Bt) do { __builtin_amdgcn_s_setprio(1); _Pragma("unroll") for (int m = 0; m < 4; ++m) _Pragma("unroll") for (int n = 0; n < 2; ++n) _Pragma("unroll") for (int k = 0; k < 2; ++k) \
;         acc[ai][bj][m][n] = __builtin_amdgcn_mfma_f32_16x16x32_bf16(Bt[n][k], At[m][k], acc[ai][bj][m][n], 0, 0, 0); __builtin_amdgcn_s_setprio(0); } while (0)
; #define PG8_WAIT_V(n) asm volatile("s_waitcnt vmcnt(" #n ")" ::: "memory")
; #define PG8_BAR __builtin_amdgcn_s_barrier()
;     __device__ __forceinline__ void operator()(const f32x4 (&acc)[2][2][4][2], const Unit& u, int wr, int wc, int fr, int fq) const {
;         const int row0 = u.pm * BM + wr * 64 + fr, col0 = u.pn * BM + wc * 32 + 8 * fq, lcol = u.pn * BM + (wc * 4 + fq) * 16;
; #pragma unroll
;         for (int ai = 0; ai < 2; ++ai) {
;             u32x4 L4[4], H4[4][2];
; #pragma unroll
;             for (int m = 0; m < 4; ++m) {
;                 const int row = row0 + ai * HALF + m * 16; const size_t off = (size_t)row * 2048 + col0, loff = (size_t)row * 2048 + lcol;
;                 L4[m] = *(const PG8_GAS u32x4*)(lin + loff); H4[m][0] = *(const PG8_GAS u32x4*)(hin + off); H4[m][1] = *(const PG8_GAS u32x4*)(hin + off + HALF);
;             }
; template <class Epi, class Sched, bool ALIGN_EPI = false, bool SP2 = false>
; __device__ __forceinline__ void gemm_phase(PG8_LAS unsigned char* lds, const Gemm g, const Sched& S, const Epi& E, const int tid) {
;     ...
;             PG8_WAIT_V(8); PG8_WAIT_L(0); PG8_BAR; PG8_MMA(0, 0, At, B0); PG8_MMA(0, 1, At, B1); PG8_BAR; PG8_SCHED;
;             PG8_LDA(At, 1, 1); PG8_STAGE(PG8_SB(1, 0), b3, voffB); PG8_STAGE(PG8_SB(1, 1), b3 + hstep, voffB); PG8_STAGE(PG8_SA(1, 0), a3, voffA);
;             PG8_WAIT_V(8); PG8_WAIT_L(0); PG8_BAR; PG8_MMA(1, 0, At, B0); PG8_MMA(1, 1, At, B1); PG8_BAR; PG8_SCHED;
	s_add_i32 s58, s77, s61
	v_lshl_add_u64 v[210:211], v[210:211], 0, s[28:29]
	s_mov_b32 m0, s58
	ds_read_b128 v[166:169], v236 offset:49152
	ds_read_b128 v[170:173], v236 offset:50176
	ds_read_b128 v[174:177], v236 offset:51200
	ds_read_b128 v[178:181], v236 offset:52224
	ds_read_b128 v[194:197], v236 offset:53248
	ds_read_b128 v[198:201], v236 offset:54272
	ds_read_b128 v[202:205], v236 offset:55296
	ds_read_b128 v[206:209], v236 offset:56320
	global_load_lds_dwordx4 v[210:211], off
	s_add_i32 m0, s58, 0x2000
	s_add_u32 s56, s56, 0x80080
	v_lshl_add_u64 v[210:211], v[212:213], 0, s[28:29]
	s_addc_u32 s57, s57, 0
	s_add_i32 s58, s78, s61
	global_load_lds_dwordx4 v[210:211], off
	v_lshl_add_u64 v[210:211], s[56:57], 0, v[96:97]
	s_mov_b32 m0, s58
	s_nop 0
	global_load_lds_dwordx4 v[210:211], off
	v_lshl_add_u64 v[210:211], s[56:57], 0, v[98:99]
	s_add_i32 m0, s58, 0x2000
	s_nop 0
	global_load_lds_dwordx4 v[210:211], off
	v_lshl_add_u64 v[210:211], v[214:215], 0, s[28:29]
	s_mov_b32 m0, s66
	s_nop 0
	global_load_lds_dwordx4 v[210:211], off
	v_lshl_add_u64 v[210:211], v[216:217], 0, s[28:29]
	s_mov_b32 m0, s67
	s_nop 0
	global_load_lds_dwordx4 v[210:211], off
	s_waitcnt vmcnt(8)
	s_waitcnt lgkmcnt(0)
	s_barrier
	s_setprio 1
	v_mfma_f32_16x16x32_bf16 v[60:63], v[126:129], v[166:169], v[60:63]
	v_mfma_f32_16x16x32_bf16 v[56:59], v[142:145], v[166:169], v[56:59]
	v_mfma_f32_16x16x32_bf16 v[44:47], v[126:129], v[174:177], v[44:47]
	v_mfma_f32_16x16x32_bf16 v[40:43], v[142:145], v[174:177], v[40:43]
	v_mfma_f32_16x16x32_bf16 v[28:31], v[126:129], v[194:197], v[28:31]
	v_mfma_f32_16x16x32_bf16 v[24:27], v[142:145], v[194:197], v[24:27]
	v_mfma_f32_16x16x32_bf16 v[12:15], v[126:129], v[202:205], v[12:15]
	v_mfma_f32_16x16x32_bf16 v[8:11], v[142:145], v[202:205], v[8:11]
	v_mfma_f32_16x16x32_bf16 v[60:63], v[130:133], v[170:173], v[60:63]
	v_mfma_f32_16x16x32_bf16 v[56:59], v[146:149], v[170:173], v[56:59]
	v_mfma_f32_16x16x32_bf16 v[44:47], v[130:133], v[178:181], v[44:47]
	v_mfma_f32_16x16x32_bf16 v[40:43], v[146:149], v[178:181], v[40:43]
	v_mfma_f32_16x16x32_bf16 v[28:31], v[130:133], v[198:201], v[28:31]
	v_mfma_f32_16x16x32_bf16 v[24:27], v[146:149], v[198:201], v[24:27]
	v_mfma_f32_16x16x32_bf16 v[12:15], v[130:133], v[206:209], v[12:15]
	v_mfma_f32_16x16x32_bf16 v[8:11], v[146:149], v[206:209], v[8:11]
	v_mfma_f32_16x16x32_bf16 v[52:55], v[150:153], v[166:169], v[52:55]
	v_mfma_f32_16x16x32_bf16 v[48:51], v[158:161], v[166:169], v[48:51]
	v_mfma_f32_16x16x32_bf16 v[36:39], v[150:153], v[174:177], v[36:39]
	v_mfma_f32_16x16x32_bf16 v[32:35], v[158:161], v[174:177], v[32:35]
	v_mfma_f32_16x16x32_bf16 v[20:23], v[150:153], v[194:197], v[20:23]
	v_mfma_f32_16x16x32_bf16 v[16:19], v[158:161], v[194:197], v[16:19]
	v_mfma_f32_16x16x32_bf16 v[4:7], v[150:153], v[202:205], v[4:7]
	v_mfma_f32_16x16x32_bf16 v[0:3], v[158:161], v[202:205], v[0:3]
	v_mfma_f32_16x16x32_bf16 v[52:55], v[154:157], v[170:173], v[52:55]
	v_mfma_f32_16x16x32_bf16 v[48:51], v[162:165], v[170:173], v[48:51]
	v_mfma_f32_16x16x32_bf16 v[36:39], v[154:157], v[178:181], v[36:39]
	v_mfma_f32_16x16x32_bf16 v[32:35], v[162:165], v[178:181], v[32:35]
	v_mfma_f32_16x16x32_bf16 v[20:23], v[154:157], v[198:201], v[20:23]
	v_mfma_f32_16x16x32_bf16 v[16:19], v[162:165], v[198:201], v[16:19]
	v_mfma_f32_16x16x32_bf16 v[4:7], v[154:157], v[206:209], v[4:7]
	v_mfma_f32_16x16x32_bf16 v[0:3], v[162:165], v[206:209], v[0:3]
	s_setprio 0
	s_barrier
	s_add_i32 s76, s76, 2
	s_add_u32 s73, s73, 0x100
	s_addc_u32 s75, s75, 0
	s_add_u32 s54, s54, 0x100
	s_addc_u32 s55, s55, 0
	s_cmp_gt_u32 s76, 29
	s_cbranch_scc0 .LBB0_1199
	v_and_b32_e32 v127, 64, v228
	v_xor_b32_e32 v126, 16, v228
	v_add_u32_e32 v127, 64, v127
	v_cmp_lt_i32_e32 vcc, v126, v127
	s_lshl_b32 s47, s69, 8
	v_lshl_add_u32 v198, s70, 8, v101
	v_cndmask_b32_e32 v126, v228, v126, vcc
	v_or_b32_e32 v194, s47, v235
	v_lshlrev_b32_e32 v238, 2, v126
	v_xor_b32_e32 v126, 32, v228
	v_or_b32_e32 v196, s47, v234
	v_ashrrev_i32_e32 v195, 31, v194
	v_cmp_lt_i32_e32 vcc, v126, v127
	v_ashrrev_i32_e32 v199, 31, v198
	v_ashrrev_i32_e32 v197, 31, v196
	v_cndmask_b32_e32 v126, v228, v126, vcc
	v_lshl_add_u64 v[202:203], s[34:35], 0, v[194:195]
	v_lshlrev_b64 v[216:217], 11, v[198:199]
	v_lshlrev_b32_e32 v237, 2, v126
	v_lshlrev_b64 v[218:219], 1, v[196:197]
	v_lshl_add_u64 v[126:127], v[202:203], 0, v[216:217]
	v_lshl_add_u64 v[200:201], s[30:31], 0, v[218:219]
	global_load_dwordx4 v[170:173], v[126:127], off
	v_lshlrev_b64 v[220:221], 12, v[198:199]
	v_lshl_add_u64 v[126:127], v[200:201], 0, v[220:221]
	global_load_dwordx4 v[178:181], v[126:127], off
	global_load_dwordx4 v[174:177], v[126:127], off offset:256
	v_or_b32_e32 v212, 16, v198
	v_ashrrev_i32_e32 v213, 31, v212
	v_lshlrev_b64 v[214:215], 11, v[212:213]
	v_lshl_add_u64 v[126:127], v[202:203], 0, v[214:215]
	v_or_b32_e32 v208, 32, v198
	global_load_dwordx4 v[158:161], v[126:127], off
	v_lshlrev_b64 v[126:127], 12, v[212:213]
	v_ashrrev_i32_e32 v209, 31, v208
	v_lshl_add_u64 v[126:127], v[200:201], 0, v[126:127]
	v_lshlrev_b64 v[210:211], 11, v[208:209]
	global_load_dwordx4 v[166:169], v[126:127], off
	global_load_dwordx4 v[162:165], v[126:127], off offset:256
	v_lshl_add_u64 v[126:127], v[202:203], 0, v[210:211]
	v_or_b32_e32 v204, 48, v198
	global_load_dwordx4 v[146:149], v[126:127], off
	v_lshlrev_b64 v[126:127], 12, v[208:209]
	v_ashrrev_i32_e32 v205, 31, v204
	v_lshl_add_u64 v[126:127], v[200:201], 0, v[126:127]
	v_lshlrev_b64 v[206:207], 11, v[204:205]
	v_lshlrev_b64 v[130:131], 12, v[204:205]
	global_load_dwordx4 v[154:157], v[126:127], off
	global_load_dwordx4 v[150:153], v[126:127], off offset:256
	v_lshl_add_u64 v[126:127], v[202:203], 0, v[206:207]
	v_lshl_add_u64 v[130:131], v[200:201], 0, v[130:131]
	global_load_dwordx4 v[126:129], v[126:127], off
	s_nop 0
	global_load_dwordx4 v[142:145], v[130:131], off
	s_nop 0
	global_load_dwordx4 v[130:133], v[130:131], off offset:256
	v_mov_b32_e32 v225, v134
	v_mov_b32_e32 v243, v136
	v_mov_b32_e32 v242, v140
	s_waitcnt vmcnt(0)
; #define PG8_GAS __attribute__((address_space(1)))
; __device__ __forceinline__ float e_x24(unsigned h16, unsigned l8) { return __uint_as_float(((h16 - (l8 >> 7)) << 16) | (l8 << 8)); }
;     __device__ __forceinline__ void operator()(const f32x4 (&acc)[2][2][4][2], const Unit& u, int wr, int wc, int fr, int fq) const {
;     ...
;             for (int m = 0; m < 4; ++m) {
;                 const int row = row0 + ai * HALF + m * 16; const size_t off = (size_t)row * 2048 + col0, loff = (size_t)row * 2048 + lcol; float ss = 0.f;
;                 const u32x4 l4 = L4[m];
;                 u32x4 lo4;
; #pragma unroll
;                 for (int bj = 0; bj < 2; ++bj) {
;                     const u32x4 h4 = H4[m][bj];
;                     u32x4 ho;
; #pragma unroll
;                     for (int j = 0; j < 4; ++j) {
;                         const unsigned lw = l4[2 * bj + (j >> 1)], lb0 = (lw >> (16 * (j & 1))) & 0xffu, lb1 = (lw >> (16 * (j & 1) + 8)) & 0xffu;
;                         const float x0 = e_x24(h4[j] & 0xffffu, lb0) + acc[ai][bj][m][j >> 1][2 * (j & 1)] * scale, x1 = e_x24(h4[j] >> 16, lb1) + acc[ai][bj][m][j >> 1][2 * (j & 1) + 1] * scale;
;                         const unsigned b0 = __float_as_uint(x0), b1 = __float_as_uint(x1);
;                         ho[j] = ((b0 + 0x8000u) >> 16) | ((b1 + 0x8000u) & 0xffff0000u);
;                         const unsigned nb = ((b0 >> 8) & 0xffu) | (b1 & 0xff00u);
;                         if ((j & 1) == 0) lo4[2 * bj + (j >> 1)] = nb; else lo4[2 * bj + (j >> 1)] |= nb << 16;
;                         ss += x0 * x0 + x1 * x1;
;                     }
;                     *(PG8_GAS u32x4*)(hout + off + bj * HALF) = ho;
	v_lshrrev_b32_sdwa v182, v229, v171 dst_sel:DWORD dst_unused:UNUSED_PAD src0_sel:DWORD src1_sel:BYTE_0
	v_lshrrev_b32_sdwa v183, v229, v170 dst_sel:DWORD dst_unused:UNUSED_PAD src0_sel:DWORD src1_sel:BYTE_0
	v_sub_u32_sdwa v183, v178, v183 dst_sel:WORD_1 dst_unused:UNUSED_PAD src0_sel:DWORD src1_sel:DWORD
	v_sub_u32_sdwa v182, v180, v182 dst_sel:WORD_1 dst_unused:UNUSED_PAD src0_sel:DWORD src1_sel:DWORD
	v_lshlrev_b32_sdwa v222, v230, v171 dst_sel:DWORD dst_unused:UNUSED_PAD src0_sel:DWORD src1_sel:BYTE_0
	v_lshlrev_b32_sdwa v224, v230, v170 dst_sel:DWORD dst_unused:UNUSED_PAD src0_sel:DWORD src1_sel:BYTE_0
	v_or_b32_e32 v223, v182, v222
	v_or_b32_e32 v222, v183, v224
	v_mov_b32_e32 v224, v138
	v_pk_add_f32 v[222:223], v[224:225], v[222:223]
	v_lshlrev_b32_e32 v182, 1, v170
	v_add_u32_e32 v134, 0x8000, v222
	v_lshrrev_b32_e32 v138, 16, v134
	v_lshlrev_b32_e32 v134, 1, v171
	v_and_b32_e32 v134, 0x10000, v134
	v_and_b32_e32 v182, 0x10000, v182
	v_sub_u32_e32 v134, v180, v134
	v_sub_u32_e32 v178, v178, v182
	v_and_b32_e32 v134, 0xffff0000, v134
	v_and_b32_e32 v178, 0xffff0000, v178
	v_and_b32_e32 v180, 0xff00, v171
	v_and_b32_e32 v182, 0xff00, v170
	v_or_b32_e32 v225, v134, v180
	v_or_b32_e32 v224, v178, v182
	v_mov_b32_e32 v134, v139
	v_pk_add_f32 v[224:225], v[134:135], v[224:225]
	v_and_b32_sdwa v135, v171, s93 dst_sel:DWORD dst_unused:UNUSED_PAD src0_sel:WORD_1 src1_sel:DWORD
	v_and_b32_sdwa v178, v170, s93 dst_sel:DWORD dst_unused:UNUSED_PAD src0_sel:WORD_1 src1_sel:DWORD
	v_lshlrev_b32_sdwa v182, v231, v170 dst_sel:DWORD dst_unused:UNUSED_PAD src0_sel:DWORD src1_sel:BYTE_3
	v_lshlrev_b32_sdwa v136, v231, v171 dst_sel:DWORD dst_unused:UNUSED_PAD src0_sel:DWORD src1_sel:BYTE_3
	v_lshrrev_b32_e32 v180, 7, v178
	v_lshrrev_b32_e32 v183, 7, v135
	v_and_b32_e32 v136, 0x10000, v136
	v_and_b32_e32 v140, 0x10000, v182
	v_sub_u32_sdwa v180, v179, v180 dst_sel:WORD_1 dst_unused:UNUSED_PAD src0_sel:DWORD src1_sel:DWORD
	v_sub_u32_sdwa v183, v181, v183 dst_sel:WORD_1 dst_unused:UNUSED_PAD src0_sel:DWORD src1_sel:DWORD
	v_lshlrev_b32_e32 v135, 8, v135
	v_lshlrev_b32_e32 v178, 8, v178
	v_sub_u32_e32 v136, v181, v136
	v_sub_u32_e32 v140, v179, v140
	v_or_b32_e32 v241, v183, v135
	v_or_b32_e32 v240, v180, v178
	v_and_b32_e32 v136, 0xffff0000, v136
	v_and_b32_e32 v140, 0xffff0000, v140
	v_lshlrev_b32_sdwa v171, v230, v171 dst_sel:DWORD dst_unused:UNUSED_PAD src0_sel:DWORD src1_sel:BYTE_3
	v_lshlrev_b32_sdwa v170, v230, v170 dst_sel:DWORD dst_unused:UNUSED_PAD src0_sel:DWORD src1_sel:BYTE_3
	v_pk_add_f32 v[240:241], v[242:243], v[240:241]
	v_or_b32_e32 v171, v136, v171
	v_or_b32_e32 v170, v140, v170
	v_mov_b32_e32 v136, v141
	v_add_u32_e32 v135, 0x8000, v240
	v_pk_add_f32 v[140:141], v[136:137], v[170:171]
	v_lshrrev_b32_e32 v135, 16, v135
	v_add_u32_e32 v136, 0x8000, v140
	v_and_or_b32 v135, v136, s90, v135
	v_pk_mul_f32 v[136:137], v[140:141], v[140:141]
	v_add_u32_e32 v178, 0x8000, v141
	v_pk_fma_f32 v[170:171], v[240:241], v[240:241], v[136:137]
	v_add_u32_e32 v136, 0x8000, v223
	v_lshrrev_b32_e32 v136, 16, v136
	v_add_u32_e32 v137, 0x8000, v225
	v_and_or_b32 v136, v137, s90, v136
	v_add_u32_e32 v137, 0x8000, v241
	v_lshrrev_b32_e32 v137, 16, v137
	v_add_u32_e32 v134, 0x8000, v224
	v_and_or_b32 v137, v178, s90, v137
	v_lshl_add_u64 v[178:179], s[30:31], 0, v[220:221]
	v_and_or_b32 v134, v134, s90, v138
	v_lshl_add_u64 v[178:179], v[178:179], 0, v[218:219]
	global_store_dwordx4 v[178:179], v[134:137], off
	v_lshlrev_b32_sdwa v182, v231, v172 dst_sel:DWORD dst_unused:UNUSED_PAD src0_sel:DWORD src1_sel:BYTE_3
	v_mov_b32_e32 v219, v120
	v_lshrrev_b32_sdwa v134, v229, v173 dst_sel:DWORD dst_unused:UNUSED_PAD src0_sel:DWORD src1_sel:BYTE_0
	v_lshrrev_b32_sdwa v135, v229, v172 dst_sel:DWORD dst_unused:UNUSED_PAD src0_sel:DWORD src1_sel:BYTE_0
	v_sub_u32_sdwa v136, v174, v135 dst_sel:WORD_1 dst_unused:UNUSED_PAD src0_sel:DWORD src1_sel:DWORD
	v_sub_u32_sdwa v134, v176, v134 dst_sel:WORD_1 dst_unused:UNUSED_PAD src0_sel:DWORD src1_sel:DWORD
	v_lshlrev_b32_sdwa v135, v230, v173 dst_sel:DWORD dst_unused:UNUSED_PAD src0_sel:DWORD src1_sel:BYTE_0
	v_lshlrev_b32_sdwa v137, v230, v172 dst_sel:DWORD dst_unused:UNUSED_PAD src0_sel:DWORD src1_sel:BYTE_0
	v_or_b32_e32 v135, v134, v135
	v_or_b32_e32 v134, v136, v137
	v_mov_b32_e32 v136, v122
	v_mov_b32_e32 v137, v118
	v_pk_add_f32 v[134:135], v[136:137], v[134:135]
	v_lshlrev_b32_e32 v122, 1, v172
; #define PG8_GAS __attribute__((address_space(1)))
; __device__ __forceinline__ float e_x24(unsigned h16, unsigned l8) { return __uint_as_float(((h16 - (l8 >> 7)) << 16) | (l8 << 8)); }
;     __device__ __forceinline__ void operator()(const f32x4 (&acc)[2][2][4][2], const Unit& u, int wr, int wc, int fr, int fq) const {
;     ...
;                     for (int j = 0; j < 4; ++j) {
;                         const unsigned lw = l4[2 * bj + (j >> 1)], lb0 = (lw >> (16 * (j & 1))) & 0xffu, lb1 = (lw >> (16 * (j & 1) + 8)) & 0xffu;
;                         const float x0 = e_x24(h4[j] & 0xffffu, lb0) + acc[ai][bj][m][j >> 1][2 * (j & 1)] * scale, x1 = e_x24(h4[j] >> 16, lb1) + acc[ai][bj][m][j >> 1][2 * (j & 1) + 1] * scale;
;                         const unsigned b0 = __float_as_uint(x0), b1 = __float_as_uint(x1);
;                         ho[j] = ((b0 + 0x8000u) >> 16) | ((b1 + 0x8000u) & 0xffff0000u);
;                         const unsigned nb = ((b0 >> 8) & 0xffu) | (b1 & 0xff00u);
;                         if ((j & 1) == 0) lo4[2 * bj + (j >> 1)] = nb; else lo4[2 * bj + (j >> 1)] |= nb << 16;
;                         ss += x0 * x0 + x1 * x1;
;                     }
;                     *(PG8_GAS u32x4*)(hout + off + bj * HALF) = ho;
;                 }
;                 *(PG8_GAS u32x4*)(lout + loff) = lo4;
;                 ss += __shfl_xor(ss, 16); ss += __shfl_xor(ss, 32);
;                 if (fq == 0) __hip_atomic_fetch_add((PG8_GAS unsigned long long*)(rowsq_out + row), (unsigned long long)(ss * 16777216.0f + 0.5f), __ATOMIC_RELAXED, __HIP_MEMORY_SCOPE_AGENT);
	v_add_u32_e32 v118, 0x8000, v134
	v_lshrrev_b32_e32 v180, 16, v118
	v_lshlrev_b32_e32 v118, 1, v173
	v_and_b32_e32 v118, 0x10000, v118
	v_and_b32_e32 v122, 0x10000, v122
	v_sub_u32_e32 v118, v176, v118
	v_sub_u32_e32 v122, v174, v122
	v_and_b32_e32 v118, 0xffff0000, v118
	v_and_b32_e32 v122, 0xffff0000, v122
	v_and_b32_e32 v136, 0xff00, v173
	v_and_b32_e32 v174, 0xff00, v172
	v_or_b32_e32 v137, v118, v136
	v_or_b32_e32 v136, v122, v174
	v_mov_b32_e32 v118, v123
	v_pk_add_f32 v[122:123], v[118:119], v[136:137]
	v_and_b32_sdwa v119, v173, s93 dst_sel:DWORD dst_unused:UNUSED_PAD src0_sel:WORD_1 src1_sel:DWORD
	v_add_u32_e32 v118, 0x8000, v122
	v_and_b32_sdwa v174, v172, s93 dst_sel:DWORD dst_unused:UNUSED_PAD src0_sel:WORD_1 src1_sel:DWORD
	v_lshlrev_b32_sdwa v120, v231, v173 dst_sel:DWORD dst_unused:UNUSED_PAD src0_sel:DWORD src1_sel:BYTE_3
	v_and_or_b32 v118, v118, s90, v180
	v_lshrrev_b32_e32 v176, 7, v174
	v_lshrrev_b32_e32 v180, 7, v119
	v_mov_b32_e32 v218, v124
	v_and_b32_e32 v120, 0x10000, v120
	v_and_b32_e32 v124, 0x10000, v182
	v_sub_u32_sdwa v176, v175, v176 dst_sel:WORD_1 dst_unused:UNUSED_PAD src0_sel:DWORD src1_sel:DWORD
	v_sub_u32_sdwa v180, v177, v180 dst_sel:WORD_1 dst_unused:UNUSED_PAD src0_sel:DWORD src1_sel:DWORD
	v_lshlrev_b32_e32 v119, 8, v119
	v_lshlrev_b32_e32 v174, 8, v174
	v_sub_u32_e32 v120, v177, v120
	v_sub_u32_e32 v124, v175, v124
	v_or_b32_e32 v181, v180, v119
	v_or_b32_e32 v180, v176, v174
	v_and_b32_e32 v120, 0xffff0000, v120
	v_and_b32_e32 v124, 0xffff0000, v124
	v_lshlrev_b32_sdwa v173, v230, v173 dst_sel:DWORD dst_unused:UNUSED_PAD src0_sel:DWORD src1_sel:BYTE_3
	v_lshlrev_b32_sdwa v172, v230, v172 dst_sel:DWORD dst_unused:UNUSED_PAD src0_sel:DWORD src1_sel:BYTE_3
	v_pk_add_f32 v[180:181], v[218:219], v[180:181]
	v_or_b32_e32 v173, v120, v173
	v_or_b32_e32 v172, v124, v172
	v_mov_b32_e32 v120, v125
	v_add_u32_e32 v119, 0x8000, v180
	v_pk_add_f32 v[124:125], v[120:121], v[172:173]
	v_lshrrev_b32_e32 v119, 16, v119
	v_add_u32_e32 v120, 0x8000, v124
	v_pk_mul_f32 v[138:139], v[224:225], v[224:225]
	v_pk_mul_f32 v[136:137], v[122:123], v[122:123]
	v_and_or_b32 v119, v120, s90, v119
	v_pk_mul_f32 v[120:121], v[124:125], v[124:125]
	v_pk_fma_f32 v[138:139], v[222:223], v[222:223], v[138:139]
	v_pk_fma_f32 v[136:137], v[134:135], v[134:135], v[136:137]
	v_pk_fma_f32 v[172:173], v[180:181], v[180:181], v[120:121]
	v_add_u32_e32 v120, 0x8000, v135
	v_lshrrev_b32_e32 v134, 8, v134
	v_lshrrev_b32_e32 v120, 16, v120
	v_add_u32_e32 v121, 0x8000, v123
	v_perm_b32 v122, v122, v134, s94
	v_add_f32_e32 v134, v138, v170
	v_and_or_b32 v120, v121, s90, v120
	v_add_u32_e32 v121, 0x8000, v181
	v_add_f32_e32 v134, v139, v134
	v_lshrrev_b32_e32 v121, 16, v121
	v_add_u32_e32 v174, 0x8000, v125
	v_add_f32_e32 v134, v171, v134
	v_and_or_b32 v121, v174, s90, v121
	v_lshrrev_b32_e32 v174, 8, v181
	v_lshrrev_b32_e32 v175, 8, v180
	v_add_f32_e32 v134, v136, v134
	v_lshrrev_b32_e32 v176, 8, v241
	v_lshrrev_b32_e32 v177, 8, v240
	v_perm_b32 v124, v124, v175, s94
	v_perm_b32 v125, v125, v174, s94
	v_lshrrev_b32_e32 v135, 8, v135
	v_lshrrev_b32_e32 v174, 8, v223
	v_lshrrev_b32_e32 v175, 8, v222
	v_add_f32_e32 v134, v172, v134
	v_perm_b32 v140, v140, v177, s94
	v_perm_b32 v141, v141, v176, s94
	v_perm_b32 v175, v224, v175, s94
	v_perm_b32 v174, v225, v174, s94
	v_perm_b32 v123, v123, v135, s94
	v_add_f32_e32 v134, v137, v134
	global_store_dwordx4 v[178:179], v[118:121], off offset:256
	v_lshl_or_b32 v125, v125, 16, v123
	v_lshl_or_b32 v124, v124, 16, v122
	v_lshl_add_u64 v[118:119], s[34:35], 0, v[216:217]
	v_lshl_or_b32 v123, v141, 16, v174
	v_lshl_or_b32 v122, v140, 16, v175
	v_add_f32_e32 v134, v173, v134
	v_lshl_add_u64 v[118:119], v[118:119], 0, v[194:195]
	global_store_dwordx4 v[118:119], v[122:125], off
	ds_bpermute_b32 v118, v238, v134
	s_waitcnt lgkmcnt(0)
	v_add_f32_e32 v118, v134, v118
	ds_bpermute_b32 v119, v237, v118
	s_and_saveexec_b64 s[54:55], s[40:41]
	s_mov_b32 s80, 0x4b800000
	s_cbranch_execz .LBB0_1202
	s_waitcnt lgkmcnt(0)
	v_add_f32_e32 v118, v118, v119
	v_fma_f32 v118, v118, s80, 0.5
	v_trunc_f32_e32 v118, v118
	v_mul_f32_e32 v119, 0x2f800000, v118
	v_floor_f32_e32 v119, v119
	v_fmac_f32_e32 v118, 0xcf800000, v119
	v_cvt_u32_f32_e32 v118, v118
	v_cvt_u32_f32_e32 v119, v119
	v_lshl_add_u64 v[120:121], v[198:199], 3, s[44:45]
	global_atomic_add_x2 v[120:121], v[118:119], off
